# weight-conversion transposes: the seven remaining item loops issue their 16 row loads per trip together and write LDS as they land (same as the k=6 w_in loop)
# baseline (speedup 1.0000x reference)
; #define LAS __attribute__((address_space(3)))
; template <int MODE> __device__ __forceinline__ void transpose_item(const float* W, int K, int N, bf16_t* WT, LAS float* scr, int item, int lane) {
;     const int nblk = N / 32, kb = item / nblk, nb = item % nblk, k0 = 64 * kb, n0 = 32 * nb;
; #pragma unroll 8
;     for (int i = 0; i < 32; ++i) { const int kk = 2 * i + (lane >> 5); scr[kk * 33 + (lane & 31)] = W[(size_t)(k0 + kk) * N + n0 + (lane & 31)]; }
; __device__ __forceinline__ void ph_wconv(CArgs& a, int l, unsigned char* ldsg, int gw, int ngw, int lane, int wv, int mask) {
;     ...
;     if (mask & 2) for (int it = gw; it < 3 * I_SQ; it += ngw) { const int wh = it / I_SQ; transpose_item<0>(a.in[27 + wh] + (size_t)l * 1048576, 1024, 1024, (bf16_t*)(ws + WS_WA + (size_t)wh * 2 * MiB), scr, it % I_SQ, lane); }
.LBB0_152:
	s_lshl_b32 s16, s10, 1
	s_lshl_b32 s14, s7, 1
	v_or_b32_e32 v18, s16, v10
	v_or_b32_e32 v16, s14, v5
	v_ashrrev_i32_e32 v19, 31, v18
	v_ashrrev_i32_e32 v17, 31, v16
	v_lshlrev_b64 v[18:19], 12, v[18:19]
	v_lshlrev_b64 v[16:17], 12, v[16:17]
	v_lshl_add_u64 v[18:19], v[8:9], 0, v[18:19]
	v_lshl_add_u64 v[16:17], v[8:9], 0, v[16:17]
	global_load_dword v44, v[18:19], off
	global_load_dword v45, v[16:17], off
	s_add_i32 s18, s16, 4
	s_add_i32 s17, s14, 4
	v_or_b32_e32 v18, s18, v10
	v_or_b32_e32 v16, s17, v5
	v_ashrrev_i32_e32 v19, 31, v18
	v_ashrrev_i32_e32 v17, 31, v16
	v_lshlrev_b64 v[18:19], 12, v[18:19]
	v_lshlrev_b64 v[16:17], 12, v[16:17]
	v_lshl_add_u64 v[18:19], v[8:9], 0, v[18:19]
	v_lshl_add_u64 v[16:17], v[8:9], 0, v[16:17]
	global_load_dword v46, v[18:19], off
	global_load_dword v47, v[16:17], off
	s_add_i32 s18, s16, 8
	s_add_i32 s17, s14, 8
	v_or_b32_e32 v18, s18, v10
	v_or_b32_e32 v16, s17, v5
	v_ashrrev_i32_e32 v19, 31, v18
	v_ashrrev_i32_e32 v17, 31, v16
	v_lshlrev_b64 v[18:19], 12, v[18:19]
	v_lshlrev_b64 v[16:17], 12, v[16:17]
	v_lshl_add_u64 v[18:19], v[8:9], 0, v[18:19]
	v_lshl_add_u64 v[16:17], v[8:9], 0, v[16:17]
	global_load_dword v48, v[18:19], off
	global_load_dword v49, v[16:17], off
	s_add_i32 s18, s16, 12
	s_add_i32 s17, s14, 12
	v_or_b32_e32 v18, s18, v10
	v_or_b32_e32 v16, s17, v5
	v_ashrrev_i32_e32 v19, 31, v18
	v_ashrrev_i32_e32 v17, 31, v16
	v_lshlrev_b64 v[18:19], 12, v[18:19]
	v_lshlrev_b64 v[16:17], 12, v[16:17]
	v_lshl_add_u64 v[18:19], v[8:9], 0, v[18:19]
	v_lshl_add_u64 v[16:17], v[8:9], 0, v[16:17]
	global_load_dword v50, v[18:19], off
	global_load_dword v51, v[16:17], off
	s_add_i32 s18, s16, 16
	s_add_i32 s17, s14, 16
	v_or_b32_e32 v18, s18, v10
	v_or_b32_e32 v16, s17, v5
	v_ashrrev_i32_e32 v19, 31, v18
	v_ashrrev_i32_e32 v17, 31, v16
	v_lshlrev_b64 v[18:19], 12, v[18:19]
	v_lshlrev_b64 v[16:17], 12, v[16:17]
	v_lshl_add_u64 v[18:19], v[8:9], 0, v[18:19]
	v_lshl_add_u64 v[16:17], v[8:9], 0, v[16:17]
	global_load_dword v52, v[18:19], off
	global_load_dword v53, v[16:17], off
	s_add_i32 s18, s16, 20
	s_add_i32 s17, s14, 20
	v_or_b32_e32 v18, s18, v10
	v_or_b32_e32 v16, s17, v5
	v_ashrrev_i32_e32 v19, 31, v18
	v_ashrrev_i32_e32 v17, 31, v16
	v_lshlrev_b64 v[18:19], 12, v[18:19]
	v_lshlrev_b64 v[16:17], 12, v[16:17]
	v_lshl_add_u64 v[18:19], v[8:9], 0, v[18:19]
	v_lshl_add_u64 v[16:17], v[8:9], 0, v[16:17]
	global_load_dword v54, v[18:19], off
	global_load_dword v55, v[16:17], off
	s_add_i32 s18, s16, 24
	s_add_i32 s17, s14, 24
	v_or_b32_e32 v18, s18, v10
	v_or_b32_e32 v16, s17, v5
	v_ashrrev_i32_e32 v19, 31, v18
	v_ashrrev_i32_e32 v17, 31, v16
	v_lshlrev_b64 v[18:19], 12, v[18:19]
	v_lshlrev_b64 v[16:17], 12, v[16:17]
	v_lshl_add_u64 v[18:19], v[8:9], 0, v[18:19]
	v_lshl_add_u64 v[16:17], v[8:9], 0, v[16:17]
	global_load_dword v56, v[18:19], off
	global_load_dword v57, v[16:17], off
	s_add_i32 s18, s16, 28
	s_add_i32 s17, s14, 28
	v_or_b32_e32 v18, s18, v10
	v_or_b32_e32 v16, s17, v5
	v_ashrrev_i32_e32 v19, 31, v18
	v_ashrrev_i32_e32 v17, 31, v16
	v_lshlrev_b64 v[18:19], 12, v[18:19]
	v_lshlrev_b64 v[16:17], 12, v[16:17]
	v_lshl_add_u64 v[18:19], v[8:9], 0, v[18:19]
	v_lshl_add_u64 v[16:17], v[8:9], 0, v[16:17]
	global_load_dword v58, v[18:19], off
	global_load_dword v59, v[16:17], off
	s_add_i32 s10, s10, 16
	s_add_i32 s7, s7, 16
	s_add_i32 s11, s11, -16
	v_or_b32_e32 v7, s14, v3
	v_or_b32_e32 v20, s16, v2
	v_mad_u64_u32 v[16:17], s[98:99], v20, s83, v[4:5]
	v_mad_u64_u32 v[18:19], s[98:99], v7, s83, v[4:5]
	s_waitcnt vmcnt(15)
	ds_write_b32 v16, v44
	s_waitcnt vmcnt(14)
	ds_write_b32 v18, v45
	s_add_i32 s18, s16, 4
	s_add_i32 s17, s14, 4
	v_or_b32_e32 v7, s17, v3
	v_or_b32_e32 v20, s18, v2
	v_mad_u64_u32 v[16:17], s[98:99], v20, s83, v[4:5]
	v_mad_u64_u32 v[18:19], s[98:99], v7, s83, v[4:5]
	s_waitcnt vmcnt(13)
	ds_write_b32 v16, v46
	s_waitcnt vmcnt(12)
	ds_write_b32 v18, v47
	s_add_i32 s18, s16, 8
	s_add_i32 s17, s14, 8
	v_or_b32_e32 v7, s17, v3
	v_or_b32_e32 v20, s18, v2
	v_mad_u64_u32 v[16:17], s[98:99], v20, s83, v[4:5]
	v_mad_u64_u32 v[18:19], s[98:99], v7, s83, v[4:5]
	s_waitcnt vmcnt(11)
	ds_write_b32 v16, v48
	s_waitcnt vmcnt(10)
	ds_write_b32 v18, v49
	s_add_i32 s18, s16, 12
	s_add_i32 s17, s14, 12
	v_or_b32_e32 v7, s17, v3
	v_or_b32_e32 v20, s18, v2
	v_mad_u64_u32 v[16:17], s[98:99], v20, s83, v[4:5]
	v_mad_u64_u32 v[18:19], s[98:99], v7, s83, v[4:5]
	s_waitcnt vmcnt(9)
	ds_write_b32 v16, v50
	s_waitcnt vmcnt(8)
	ds_write_b32 v18, v51
	s_add_i32 s18, s16, 16
	s_add_i32 s17, s14, 16
	v_or_b32_e32 v7, s17, v3
	v_or_b32_e32 v20, s18, v2
	v_mad_u64_u32 v[16:17], s[98:99], v20, s83, v[4:5]
	v_mad_u64_u32 v[18:19], s[98:99], v7, s83, v[4:5]
	s_waitcnt vmcnt(7)
	ds_write_b32 v16, v52
	s_waitcnt vmcnt(6)
	ds_write_b32 v18, v53
	s_add_i32 s18, s16, 20
	s_add_i32 s17, s14, 20
	v_or_b32_e32 v7, s17, v3
	v_or_b32_e32 v20, s18, v2
	v_mad_u64_u32 v[16:17], s[98:99], v20, s83, v[4:5]
	v_mad_u64_u32 v[18:19], s[98:99], v7, s83, v[4:5]
	s_waitcnt vmcnt(5)
	ds_write_b32 v16, v54
	s_waitcnt vmcnt(4)
	ds_write_b32 v18, v55
	s_add_i32 s18, s16, 24
	s_add_i32 s17, s14, 24
	v_or_b32_e32 v7, s17, v3
	v_or_b32_e32 v20, s18, v2
	v_mad_u64_u32 v[16:17], s[98:99], v20, s83, v[4:5]
	v_mad_u64_u32 v[18:19], s[98:99], v7, s83, v[4:5]
	s_waitcnt vmcnt(3)
	ds_write_b32 v16, v56
	s_waitcnt vmcnt(2)
	ds_write_b32 v18, v57
	s_add_i32 s18, s16, 28
	s_add_i32 s17, s14, 28
	v_or_b32_e32 v7, s17, v3
	v_or_b32_e32 v20, s18, v2
	v_mad_u64_u32 v[16:17], s[98:99], v20, s83, v[4:5]
	v_mad_u64_u32 v[18:19], s[98:99], v7, s83, v[4:5]
	s_waitcnt vmcnt(1)
	ds_write_b32 v16, v58
	s_waitcnt vmcnt(0)
	ds_write_b32 v18, v59
	s_cmp_lg_u32 s11, 0
	s_cbranch_scc1 .LBB0_152
; #define LAS __attribute__((address_space(3)))
; __device__ __forceinline__ unsigned pkbf(float lo, float hi) { f32x2 v = {lo, hi}; bf16x2v b = __builtin_convertvector(v, bf16x2v); return __builtin_bit_cast(unsigned, b); }
; template <int MODE> __device__ __forceinline__ void transpose_item(const float* W, int K, int N, bf16_t* WT, LAS float* scr, int item, int lane) {
;     ...
;     asm volatile("s_waitcnt lgkmcnt(0)" ::: "memory");
;     const int c = lane & 7;
; #pragma unroll
;     for (int j = 0; j < 4; ++j) {
;         const int n = (lane >> 3) + 8 * j, gn = n0 + n; const LAS float* s = scr + (8 * c) * 33 + n;
;         const int drow = MODE == 0 ? gn : (MODE == 1 ? (gn >= 8608 ? gn + 96 : gn) : (gn < DFF ? 2 * gn : 2 * (gn - DFF) + 1));
;         u32x4 o; o.x = pkbf(s[0 * 33], s[1 * 33]); o.y = pkbf(s[2 * 33], s[3 * 33]); o.z = pkbf(s[4 * 33], s[5 * 33]); o.w = pkbf(s[6 * 33], s[7 * 33]);
;         *(u32x4*)(WT + (size_t)drow * K + k0 + 8 * c) = o;
;     }
;     asm volatile("s_waitcnt lgkmcnt(0)" ::: "memory");
; __device__ __forceinline__ void ph_wconv(CArgs& a, int l, unsigned char* ldsg, int gw, int ngw, int lane, int wv, int mask) {
;     ...
;     if (mask & 2) for (int it = gw; it < 3 * I_SQ; it += ngw) { const int wh = it / I_SQ; transpose_item<0>(a.in[27 + wh] + (size_t)l * 1048576, 1024, 1024, (bf16_t*)(ws + WS_WA + (size_t)wh * 2 * MiB), scr, it % I_SQ, lane); }
	s_lshl_b64 s[10:11], s[42:43], 21
	s_add_u32 s7, s4, s10
	s_waitcnt lgkmcnt(0)
	s_addc_u32 s14, s5, s11
	s_ashr_i32 s45, s44, 31
	ds_read2_b32 v[22:23], v12 offset0:33 offset1:41
	ds_read2_b32 v[24:25], v12 offset1:8
	ds_read2_b32 v[26:27], v12 offset0:66 offset1:74
	ds_read2_b32 v[28:29], v12 offset0:99 offset1:107
	ds_read2_b32 v[30:31], v12 offset0:132 offset1:140
	ds_read2_b32 v[32:33], v12 offset0:165 offset1:173
	ds_read2_b32 v[34:35], v12 offset0:198 offset1:206
	ds_read2_b32 v[36:37], v12 offset0:231 offset1:239
	s_lshl_b64 s[10:11], s[44:45], 1
	s_add_u32 s10, s7, s10
	v_or_b32_e32 v20, s40, v11
	s_addc_u32 s11, s14, s11
	v_mov_b32_e32 v7, v1
	v_ashrrev_i32_e32 v21, 31, v20
	v_lshl_add_u64 v[8:9], s[10:11], 0, v[6:7]
	v_lshlrev_b64 v[20:21], 11, v[20:21]
	s_waitcnt lgkmcnt(6)
	v_cvt_pk_bf16_f32 v16, v24, v22
	s_waitcnt lgkmcnt(4)
	v_cvt_pk_bf16_f32 v17, v26, v28
	s_waitcnt lgkmcnt(2)
	v_cvt_pk_bf16_f32 v18, v30, v32
	s_waitcnt lgkmcnt(0)
	v_cvt_pk_bf16_f32 v19, v34, v36
	v_lshl_add_u64 v[20:21], v[8:9], 0, v[20:21]
	global_store_dwordx4 v[20:21], v[16:19], off
	v_or_b32_e32 v20, s40, v13
	v_ashrrev_i32_e32 v21, 31, v20
	v_lshlrev_b64 v[20:21], 11, v[20:21]
	v_cvt_pk_bf16_f32 v16, v25, v23
	v_cvt_pk_bf16_f32 v17, v27, v29
	v_cvt_pk_bf16_f32 v18, v31, v33
	v_cvt_pk_bf16_f32 v19, v35, v37
	v_lshl_add_u64 v[20:21], v[8:9], 0, v[20:21]
	global_store_dwordx4 v[20:21], v[16:19], off
	ds_read2_b32 v[22:23], v12 offset0:49 offset1:57
	ds_read2_b32 v[24:25], v12 offset0:16 offset1:24
	ds_read2_b32 v[26:27], v12 offset0:82 offset1:90
	ds_read2_b32 v[28:29], v12 offset0:115 offset1:123
	ds_read2_b32 v[30:31], v12 offset0:148 offset1:156
	ds_read2_b32 v[32:33], v12 offset0:181 offset1:189
	ds_read2_b32 v[34:35], v12 offset0:214 offset1:222
	ds_read2_b32 v[36:37], v12 offset0:247 offset1:255
	v_or_b32_e32 v20, s40, v14
	v_ashrrev_i32_e32 v21, 31, v20
	v_lshlrev_b64 v[20:21], 11, v[20:21]
	s_waitcnt lgkmcnt(6)
	v_cvt_pk_bf16_f32 v16, v24, v22
	s_waitcnt lgkmcnt(4)
	v_cvt_pk_bf16_f32 v17, v26, v28
	s_waitcnt lgkmcnt(2)
	v_cvt_pk_bf16_f32 v18, v30, v32
	s_waitcnt lgkmcnt(0)
	v_cvt_pk_bf16_f32 v19, v34, v36
	v_lshl_add_u64 v[20:21], v[8:9], 0, v[20:21]
	global_store_dwordx4 v[20:21], v[16:19], off
	v_or_b32_e32 v20, s40, v15
	v_ashrrev_i32_e32 v21, 31, v20
	v_lshlrev_b64 v[20:21], 11, v[20:21]
	v_cvt_pk_bf16_f32 v16, v25, v23
	v_cvt_pk_bf16_f32 v17, v27, v29
	v_cvt_pk_bf16_f32 v18, v31, v33
	v_cvt_pk_bf16_f32 v19, v35, v37
	v_lshl_add_u64 v[8:9], v[8:9], 0, v[20:21]
	global_store_dwordx4 v[8:9], v[16:19], off
	s_waitcnt lgkmcnt(0)
	s_add_i32 s6, s6, s80
	s_cmpk_gt_i32 s6, 0x5ff
	s_cbranch_scc0 .LBB0_151

; template <int MODE> __device__ __forceinline__ void transpose_item(const float* W, int K, int N, bf16_t* WT, LAS float* scr, int item, int lane) {
;     const int nblk = N / 32, kb = item / nblk, nb = item % nblk, k0 = 64 * kb, n0 = 32 * nb;
; #pragma unroll 8
;     for (int i = 0; i < 32; ++i) { const int kk = 2 * i + (lane >> 5); scr[kk * 33 + (lane & 31)] = W[(size_t)(k0 + kk) * N + n0 + (lane & 31)]; }
.LBB0_159:
	s_lshl_b32 s17, s11, 1
	s_lshl_b32 s16, s10, 1
	v_or_b32_e32 v18, s17, v10
	v_or_b32_e32 v16, s16, v5
	v_ashrrev_i32_e32 v19, 31, v18
	v_ashrrev_i32_e32 v17, 31, v16
	v_lshlrev_b64 v[18:19], 12, v[18:19]
	v_lshlrev_b64 v[16:17], 12, v[16:17]
	v_lshl_add_u64 v[18:19], v[8:9], 0, v[18:19]
	v_lshl_add_u64 v[16:17], v[8:9], 0, v[16:17]
	global_load_dword v44, v[18:19], off
	global_load_dword v45, v[16:17], off
	s_add_i32 s27, s17, 4
	s_add_i32 s18, s16, 4
	v_or_b32_e32 v18, s27, v10
	v_or_b32_e32 v16, s18, v5
	v_ashrrev_i32_e32 v19, 31, v18
	v_ashrrev_i32_e32 v17, 31, v16
	v_lshlrev_b64 v[18:19], 12, v[18:19]
	v_lshlrev_b64 v[16:17], 12, v[16:17]
	v_lshl_add_u64 v[18:19], v[8:9], 0, v[18:19]
	v_lshl_add_u64 v[16:17], v[8:9], 0, v[16:17]
	global_load_dword v46, v[18:19], off
	global_load_dword v47, v[16:17], off
	s_add_i32 s27, s17, 8
	s_add_i32 s18, s16, 8
	v_or_b32_e32 v18, s27, v10
	v_or_b32_e32 v16, s18, v5
	v_ashrrev_i32_e32 v19, 31, v18
	v_ashrrev_i32_e32 v17, 31, v16
	v_lshlrev_b64 v[18:19], 12, v[18:19]
	v_lshlrev_b64 v[16:17], 12, v[16:17]
	v_lshl_add_u64 v[18:19], v[8:9], 0, v[18:19]
	v_lshl_add_u64 v[16:17], v[8:9], 0, v[16:17]
	global_load_dword v48, v[18:19], off
	global_load_dword v49, v[16:17], off
	s_add_i32 s27, s17, 12
	s_add_i32 s18, s16, 12
	v_or_b32_e32 v18, s27, v10
	v_or_b32_e32 v16, s18, v5
	v_ashrrev_i32_e32 v19, 31, v18
	v_ashrrev_i32_e32 v17, 31, v16
	v_lshlrev_b64 v[18:19], 12, v[18:19]
	v_lshlrev_b64 v[16:17], 12, v[16:17]
	v_lshl_add_u64 v[18:19], v[8:9], 0, v[18:19]
	v_lshl_add_u64 v[16:17], v[8:9], 0, v[16:17]
	global_load_dword v50, v[18:19], off
	global_load_dword v51, v[16:17], off
	s_add_i32 s27, s17, 16
	s_add_i32 s18, s16, 16
	v_or_b32_e32 v18, s27, v10
	v_or_b32_e32 v16, s18, v5
	v_ashrrev_i32_e32 v19, 31, v18
	v_ashrrev_i32_e32 v17, 31, v16
	v_lshlrev_b64 v[18:19], 12, v[18:19]
	v_lshlrev_b64 v[16:17], 12, v[16:17]
	v_lshl_add_u64 v[18:19], v[8:9], 0, v[18:19]
	v_lshl_add_u64 v[16:17], v[8:9], 0, v[16:17]
	global_load_dword v52, v[18:19], off
	global_load_dword v53, v[16:17], off
	s_add_i32 s27, s17, 20
	s_add_i32 s18, s16, 20
	v_or_b32_e32 v18, s27, v10
	v_or_b32_e32 v16, s18, v5
	v_ashrrev_i32_e32 v19, 31, v18
	v_ashrrev_i32_e32 v17, 31, v16
	v_lshlrev_b64 v[18:19], 12, v[18:19]
	v_lshlrev_b64 v[16:17], 12, v[16:17]
	v_lshl_add_u64 v[18:19], v[8:9], 0, v[18:19]
	v_lshl_add_u64 v[16:17], v[8:9], 0, v[16:17]
	global_load_dword v54, v[18:19], off
	global_load_dword v55, v[16:17], off
	s_add_i32 s27, s17, 24
	s_add_i32 s18, s16, 24
	v_or_b32_e32 v18, s27, v10
	v_or_b32_e32 v16, s18, v5
	v_ashrrev_i32_e32 v19, 31, v18
	v_ashrrev_i32_e32 v17, 31, v16
	v_lshlrev_b64 v[18:19], 12, v[18:19]
	v_lshlrev_b64 v[16:17], 12, v[16:17]
	v_lshl_add_u64 v[18:19], v[8:9], 0, v[18:19]
	v_lshl_add_u64 v[16:17], v[8:9], 0, v[16:17]
	global_load_dword v56, v[18:19], off
	global_load_dword v57, v[16:17], off
	s_add_i32 s27, s17, 28
	s_add_i32 s18, s16, 28
	v_or_b32_e32 v18, s27, v10
	v_or_b32_e32 v16, s18, v5
	v_ashrrev_i32_e32 v19, 31, v18
	v_ashrrev_i32_e32 v17, 31, v16
	v_lshlrev_b64 v[18:19], 12, v[18:19]
	v_lshlrev_b64 v[16:17], 12, v[16:17]
	v_lshl_add_u64 v[18:19], v[8:9], 0, v[18:19]
	v_lshl_add_u64 v[16:17], v[8:9], 0, v[16:17]
	global_load_dword v58, v[18:19], off
	global_load_dword v59, v[16:17], off
	s_add_i32 s11, s11, 16
	s_add_i32 s10, s10, 16
	s_add_i32 s14, s14, -16
	v_or_b32_e32 v7, s16, v3
	v_or_b32_e32 v20, s17, v2
	v_mad_u64_u32 v[16:17], s[98:99], v20, s83, v[4:5]
	v_mad_u64_u32 v[18:19], s[98:99], v7, s83, v[4:5]
	s_waitcnt vmcnt(15)
	ds_write_b32 v16, v44
	s_waitcnt vmcnt(14)
	ds_write_b32 v18, v45
	s_add_i32 s27, s17, 4
	s_add_i32 s18, s16, 4
	v_or_b32_e32 v7, s18, v3
	v_or_b32_e32 v20, s27, v2
	v_mad_u64_u32 v[16:17], s[98:99], v20, s83, v[4:5]
	v_mad_u64_u32 v[18:19], s[98:99], v7, s83, v[4:5]
	s_waitcnt vmcnt(13)
	ds_write_b32 v16, v46
	s_waitcnt vmcnt(12)
	ds_write_b32 v18, v47
	s_add_i32 s27, s17, 8
	s_add_i32 s18, s16, 8
	v_or_b32_e32 v7, s18, v3
	v_or_b32_e32 v20, s27, v2
	v_mad_u64_u32 v[16:17], s[98:99], v20, s83, v[4:5]
	v_mad_u64_u32 v[18:19], s[98:99], v7, s83, v[4:5]
	s_waitcnt vmcnt(11)
	ds_write_b32 v16, v48
	s_waitcnt vmcnt(10)
	ds_write_b32 v18, v49
	s_add_i32 s27, s17, 12
	s_add_i32 s18, s16, 12
	v_or_b32_e32 v7, s18, v3
	v_or_b32_e32 v20, s27, v2
	v_mad_u64_u32 v[16:17], s[98:99], v20, s83, v[4:5]
	v_mad_u64_u32 v[18:19], s[98:99], v7, s83, v[4:5]
	s_waitcnt vmcnt(9)
	ds_write_b32 v16, v50
	s_waitcnt vmcnt(8)
	ds_write_b32 v18, v51
	s_add_i32 s27, s17, 16
	s_add_i32 s18, s16, 16
	v_or_b32_e32 v7, s18, v3
	v_or_b32_e32 v20, s27, v2
	v_mad_u64_u32 v[16:17], s[98:99], v20, s83, v[4:5]
	v_mad_u64_u32 v[18:19], s[98:99], v7, s83, v[4:5]
	s_waitcnt vmcnt(7)
	ds_write_b32 v16, v52
	s_waitcnt vmcnt(6)
	ds_write_b32 v18, v53
	s_add_i32 s27, s17, 20
	s_add_i32 s18, s16, 20
	v_or_b32_e32 v7, s18, v3
	v_or_b32_e32 v20, s27, v2
	v_mad_u64_u32 v[16:17], s[98:99], v20, s83, v[4:5]
	v_mad_u64_u32 v[18:19], s[98:99], v7, s83, v[4:5]
	s_waitcnt vmcnt(5)
	ds_write_b32 v16, v54
	s_waitcnt vmcnt(4)
	ds_write_b32 v18, v55
	s_add_i32 s27, s17, 24
	s_add_i32 s18, s16, 24
	v_or_b32_e32 v7, s18, v3
	v_or_b32_e32 v20, s27, v2
	v_mad_u64_u32 v[16:17], s[98:99], v20, s83, v[4:5]
	v_mad_u64_u32 v[18:19], s[98:99], v7, s83, v[4:5]
	s_waitcnt vmcnt(3)
	ds_write_b32 v16, v56
	s_waitcnt vmcnt(2)
	ds_write_b32 v18, v57
	s_add_i32 s27, s17, 28
	s_add_i32 s18, s16, 28
	v_or_b32_e32 v7, s18, v3
	v_or_b32_e32 v20, s27, v2
	v_mad_u64_u32 v[16:17], s[98:99], v20, s83, v[4:5]
	v_mad_u64_u32 v[18:19], s[98:99], v7, s83, v[4:5]
	s_waitcnt vmcnt(1)
	ds_write_b32 v16, v58
	s_waitcnt vmcnt(0)
	ds_write_b32 v18, v59
	s_cmp_lg_u32 s14, 0
	s_cbranch_scc1 .LBB0_159
; #define LAS __attribute__((address_space(3)))
; __device__ __forceinline__ unsigned pkbf(float lo, float hi) { f32x2 v = {lo, hi}; bf16x2v b = __builtin_convertvector(v, bf16x2v); return __builtin_bit_cast(unsigned, b); }
; template <int MODE> __device__ __forceinline__ void transpose_item(const float* W, int K, int N, bf16_t* WT, LAS float* scr, int item, int lane) {
;     ...
;     asm volatile("s_waitcnt lgkmcnt(0)" ::: "memory");
;     const int c = lane & 7;
; #pragma unroll
;     for (int j = 0; j < 4; ++j) {
;         const int n = (lane >> 3) + 8 * j, gn = n0 + n; const LAS float* s = scr + (8 * c) * 33 + n;
;         const int drow = MODE == 0 ? gn : (MODE == 1 ? (gn >= 8608 ? gn + 96 : gn) : (gn < DFF ? 2 * gn : 2 * (gn - DFF) + 1));
;         u32x4 o; o.x = pkbf(s[0 * 33], s[1 * 33]); o.y = pkbf(s[2 * 33], s[3 * 33]); o.z = pkbf(s[4 * 33], s[5 * 33]); o.w = pkbf(s[6 * 33], s[7 * 33]);
;         *(u32x4*)(WT + (size_t)drow * K + k0 + 8 * c) = o;
;     }
;     asm volatile("s_waitcnt lgkmcnt(0)" ::: "memory");
; __device__ __forceinline__ void ph_wconv(CArgs& a, int l, unsigned char* ldsg, int gw, int ngw, int lane, int wv, int mask) {
;     ...
;     if (mask & 2) for (int it = gw; it < 3 * I_SQ; it += ngw) { const int wh = it / I_SQ; transpose_item<0>(a.in[27 + wh] + (size_t)l * 1048576, 1024, 1024, (bf16_t*)(ws + WS_WA + (size_t)wh * 2 * MiB), scr, it % I_SQ, lane); }
	s_lshl_b64 s[10:11], s[42:43], 21
	s_add_u32 s14, s6, s10
	s_waitcnt lgkmcnt(0)
	s_addc_u32 s16, s7, s11
	s_ashr_i32 s45, s44, 31
	ds_read2_b32 v[22:23], v12 offset0:33 offset1:41
	ds_read2_b32 v[24:25], v12 offset1:8
	ds_read2_b32 v[26:27], v12 offset0:66 offset1:74
	ds_read2_b32 v[28:29], v12 offset0:99 offset1:107
	ds_read2_b32 v[30:31], v12 offset0:132 offset1:140
	ds_read2_b32 v[32:33], v12 offset0:165 offset1:173
	ds_read2_b32 v[34:35], v12 offset0:198 offset1:206
	ds_read2_b32 v[36:37], v12 offset0:231 offset1:239
	s_lshl_b64 s[10:11], s[44:45], 1
	s_add_u32 s10, s14, s10
	v_or_b32_e32 v20, s40, v11
	s_addc_u32 s11, s16, s11
	v_mov_b32_e32 v7, v1
	v_ashrrev_i32_e32 v21, 31, v20
	v_lshl_add_u64 v[8:9], s[10:11], 0, v[6:7]
	v_lshlrev_b64 v[20:21], 11, v[20:21]
	s_waitcnt lgkmcnt(6)
	v_cvt_pk_bf16_f32 v16, v24, v22
	s_waitcnt lgkmcnt(4)
	v_cvt_pk_bf16_f32 v17, v26, v28
	s_waitcnt lgkmcnt(2)
	v_cvt_pk_bf16_f32 v18, v30, v32
	s_waitcnt lgkmcnt(0)
	v_cvt_pk_bf16_f32 v19, v34, v36
	v_lshl_add_u64 v[20:21], v[8:9], 0, v[20:21]
	global_store_dwordx4 v[20:21], v[16:19], off
	v_or_b32_e32 v20, s40, v13
	v_ashrrev_i32_e32 v21, 31, v20
	v_lshlrev_b64 v[20:21], 11, v[20:21]
	v_cvt_pk_bf16_f32 v16, v25, v23
	v_cvt_pk_bf16_f32 v17, v27, v29
	v_cvt_pk_bf16_f32 v18, v31, v33
	v_cvt_pk_bf16_f32 v19, v35, v37
	v_lshl_add_u64 v[20:21], v[8:9], 0, v[20:21]
	global_store_dwordx4 v[20:21], v[16:19], off
	ds_read2_b32 v[22:23], v12 offset0:49 offset1:57
	ds_read2_b32 v[24:25], v12 offset0:16 offset1:24
	ds_read2_b32 v[26:27], v12 offset0:82 offset1:90
	ds_read2_b32 v[28:29], v12 offset0:115 offset1:123
	ds_read2_b32 v[30:31], v12 offset0:148 offset1:156
	ds_read2_b32 v[32:33], v12 offset0:181 offset1:189
	ds_read2_b32 v[34:35], v12 offset0:214 offset1:222
	ds_read2_b32 v[36:37], v12 offset0:247 offset1:255
	v_or_b32_e32 v20, s40, v14
	v_ashrrev_i32_e32 v21, 31, v20
	v_lshlrev_b64 v[20:21], 11, v[20:21]
	s_waitcnt lgkmcnt(6)
	v_cvt_pk_bf16_f32 v16, v24, v22
	s_waitcnt lgkmcnt(4)
	v_cvt_pk_bf16_f32 v17, v26, v28
	s_waitcnt lgkmcnt(2)
	v_cvt_pk_bf16_f32 v18, v30, v32
	s_waitcnt lgkmcnt(0)
	v_cvt_pk_bf16_f32 v19, v34, v36
	v_lshl_add_u64 v[20:21], v[8:9], 0, v[20:21]
	global_store_dwordx4 v[20:21], v[16:19], off
	v_or_b32_e32 v20, s40, v15
	v_ashrrev_i32_e32 v21, 31, v20
	v_lshlrev_b64 v[20:21], 11, v[20:21]
	v_cvt_pk_bf16_f32 v16, v25, v23
	v_cvt_pk_bf16_f32 v17, v27, v29
	v_cvt_pk_bf16_f32 v18, v31, v33
	v_cvt_pk_bf16_f32 v19, v35, v37
	v_lshl_add_u64 v[8:9], v[8:9], 0, v[20:21]
	global_store_dwordx4 v[8:9], v[16:19], off
	s_waitcnt lgkmcnt(0)
	s_add_i32 s1, s3, s1
	s_cmpk_gt_i32 s1, 0x5ff
	s_cbranch_scc0 .LBB0_158

; template <int MODE> __device__ __forceinline__ void transpose_item(const float* W, int K, int N, bf16_t* WT, LAS float* scr, int item, int lane) {
;     const int nblk = N / 32, kb = item / nblk, nb = item % nblk, k0 = 64 * kb, n0 = 32 * nb;
; #pragma unroll 8
;     for (int i = 0; i < 32; ++i) { const int kk = 2 * i + (lane >> 5); scr[kk * 33 + (lane & 31)] = W[(size_t)(k0 + kk) * N + n0 + (lane & 31)]; }
.LBB0_234:
	s_lshl_b32 s7, s4, 1
	s_lshl_b32 s6, s3, 1
	v_or_b32_e32 v18, s7, v0
	v_or_b32_e32 v20, s6, v7
	v_mad_i64_i32 v[18:19], s[98:99], v18, s13, v[10:11]
	v_mad_i64_i32 v[20:21], s[98:99], v20, s13, v[10:11]
	global_load_dword v44, v[18:19], off
	global_load_dword v45, v[20:21], off
	s_add_i32 s11, s7, 4
	s_add_i32 s10, s6, 4
	v_or_b32_e32 v18, s11, v0
	v_or_b32_e32 v20, s10, v7
	v_mad_i64_i32 v[18:19], s[98:99], v18, s13, v[10:11]
	v_mad_i64_i32 v[20:21], s[98:99], v20, s13, v[10:11]
	global_load_dword v46, v[18:19], off
	global_load_dword v47, v[20:21], off
	s_add_i32 s11, s7, 8
	s_add_i32 s10, s6, 8
	v_or_b32_e32 v18, s11, v0
	v_or_b32_e32 v20, s10, v7
	v_mad_i64_i32 v[18:19], s[98:99], v18, s13, v[10:11]
	v_mad_i64_i32 v[20:21], s[98:99], v20, s13, v[10:11]
	global_load_dword v48, v[18:19], off
	global_load_dword v49, v[20:21], off
	s_add_i32 s11, s7, 12
	s_add_i32 s10, s6, 12
	v_or_b32_e32 v18, s11, v0
	v_or_b32_e32 v20, s10, v7
	v_mad_i64_i32 v[18:19], s[98:99], v18, s13, v[10:11]
	v_mad_i64_i32 v[20:21], s[98:99], v20, s13, v[10:11]
	global_load_dword v50, v[18:19], off
	global_load_dword v51, v[20:21], off
	s_add_i32 s11, s7, 16
	s_add_i32 s10, s6, 16
	v_or_b32_e32 v18, s11, v0
	v_or_b32_e32 v20, s10, v7
	v_mad_i64_i32 v[18:19], s[98:99], v18, s13, v[10:11]
	v_mad_i64_i32 v[20:21], s[98:99], v20, s13, v[10:11]
	global_load_dword v52, v[18:19], off
	global_load_dword v53, v[20:21], off
	s_add_i32 s11, s7, 20
	s_add_i32 s10, s6, 20
	v_or_b32_e32 v18, s11, v0
	v_or_b32_e32 v20, s10, v7
	v_mad_i64_i32 v[18:19], s[98:99], v18, s13, v[10:11]
	v_mad_i64_i32 v[20:21], s[98:99], v20, s13, v[10:11]
	global_load_dword v54, v[18:19], off
	global_load_dword v55, v[20:21], off
	s_add_i32 s11, s7, 24
	s_add_i32 s10, s6, 24
	v_or_b32_e32 v18, s11, v0
	v_or_b32_e32 v20, s10, v7
	v_mad_i64_i32 v[18:19], s[98:99], v18, s13, v[10:11]
	v_mad_i64_i32 v[20:21], s[98:99], v20, s13, v[10:11]
	global_load_dword v56, v[18:19], off
	global_load_dword v57, v[20:21], off
	s_add_i32 s11, s7, 28
	s_add_i32 s10, s6, 28
	v_or_b32_e32 v18, s11, v0
	v_or_b32_e32 v20, s10, v7
	v_mad_i64_i32 v[18:19], s[98:99], v18, s13, v[10:11]
	v_mad_i64_i32 v[20:21], s[98:99], v20, s13, v[10:11]
	global_load_dword v58, v[18:19], off
	global_load_dword v59, v[20:21], off
	s_add_i32 s4, s4, 16
	s_add_i32 s3, s3, 16
	s_add_i32 s5, s5, -16
	v_or_b32_e32 v17, s6, v3
	v_or_b32_e32 v22, s7, v2
	v_mad_u64_u32 v[18:19], s[98:99], v22, s83, v[6:7]
	v_mad_u64_u32 v[20:21], s[98:99], v17, s83, v[6:7]
	s_waitcnt vmcnt(15)
	ds_write_b32 v18, v44
	s_waitcnt vmcnt(14)
	ds_write_b32 v20, v45
	s_add_i32 s11, s7, 4
	s_add_i32 s10, s6, 4
	v_or_b32_e32 v17, s10, v3
	v_or_b32_e32 v22, s11, v2
	v_mad_u64_u32 v[18:19], s[98:99], v22, s83, v[6:7]
	v_mad_u64_u32 v[20:21], s[98:99], v17, s83, v[6:7]
	s_waitcnt vmcnt(13)
	ds_write_b32 v18, v46
	s_waitcnt vmcnt(12)
	ds_write_b32 v20, v47
	s_add_i32 s11, s7, 8
	s_add_i32 s10, s6, 8
	v_or_b32_e32 v17, s10, v3
	v_or_b32_e32 v22, s11, v2
	v_mad_u64_u32 v[18:19], s[98:99], v22, s83, v[6:7]
	v_mad_u64_u32 v[20:21], s[98:99], v17, s83, v[6:7]
	s_waitcnt vmcnt(11)
	ds_write_b32 v18, v48
	s_waitcnt vmcnt(10)
	ds_write_b32 v20, v49
	s_add_i32 s11, s7, 12
	s_add_i32 s10, s6, 12
	v_or_b32_e32 v17, s10, v3
	v_or_b32_e32 v22, s11, v2
	v_mad_u64_u32 v[18:19], s[98:99], v22, s83, v[6:7]
	v_mad_u64_u32 v[20:21], s[98:99], v17, s83, v[6:7]
	s_waitcnt vmcnt(9)
	ds_write_b32 v18, v50
	s_waitcnt vmcnt(8)
	ds_write_b32 v20, v51
	s_add_i32 s11, s7, 16
	s_add_i32 s10, s6, 16
	v_or_b32_e32 v17, s10, v3
	v_or_b32_e32 v22, s11, v2
	v_mad_u64_u32 v[18:19], s[98:99], v22, s83, v[6:7]
	v_mad_u64_u32 v[20:21], s[98:99], v17, s83, v[6:7]
	s_waitcnt vmcnt(7)
	ds_write_b32 v18, v52
	s_waitcnt vmcnt(6)
	ds_write_b32 v20, v53
	s_add_i32 s11, s7, 20
	s_add_i32 s10, s6, 20
	v_or_b32_e32 v17, s10, v3
	v_or_b32_e32 v22, s11, v2
	v_mad_u64_u32 v[18:19], s[98:99], v22, s83, v[6:7]
	v_mad_u64_u32 v[20:21], s[98:99], v17, s83, v[6:7]
	s_waitcnt vmcnt(5)
	ds_write_b32 v18, v54
	s_waitcnt vmcnt(4)
	ds_write_b32 v20, v55
	s_add_i32 s11, s7, 24
	s_add_i32 s10, s6, 24
	v_or_b32_e32 v17, s10, v3
	v_or_b32_e32 v22, s11, v2
	v_mad_u64_u32 v[18:19], s[98:99], v22, s83, v[6:7]
	v_mad_u64_u32 v[20:21], s[98:99], v17, s83, v[6:7]
	s_waitcnt vmcnt(3)
	ds_write_b32 v18, v56
	s_waitcnt vmcnt(2)
	ds_write_b32 v20, v57
	s_add_i32 s11, s7, 28
	s_add_i32 s10, s6, 28
	v_or_b32_e32 v17, s10, v3
	v_or_b32_e32 v22, s11, v2
	v_mad_u64_u32 v[18:19], s[98:99], v22, s83, v[6:7]
	v_mad_u64_u32 v[20:21], s[98:99], v17, s83, v[6:7]
	s_waitcnt vmcnt(1)
	ds_write_b32 v18, v58
	s_waitcnt vmcnt(0)
	ds_write_b32 v20, v59
	s_cmp_lg_u32 s5, 0
	s_cbranch_scc1 .LBB0_234
; #define LAS __attribute__((address_space(3)))
; __device__ __forceinline__ unsigned pkbf(float lo, float hi) { f32x2 v = {lo, hi}; bf16x2v b = __builtin_convertvector(v, bf16x2v); return __builtin_bit_cast(unsigned, b); }
; template <int MODE> __device__ __forceinline__ void transpose_item(const float* W, int K, int N, bf16_t* WT, LAS float* scr, int item, int lane) {
;     ...
;     asm volatile("s_waitcnt lgkmcnt(0)" ::: "memory");
;     const int c = lane & 7;
; #pragma unroll
;     for (int j = 0; j < 4; ++j) {
;         const int n = (lane >> 3) + 8 * j, gn = n0 + n; const LAS float* s = scr + (8 * c) * 33 + n;
;         const int drow = MODE == 0 ? gn : (MODE == 1 ? (gn >= 8608 ? gn + 96 : gn) : (gn < DFF ? 2 * gn : 2 * (gn - DFF) + 1));
;         u32x4 o; o.x = pkbf(s[0 * 33], s[1 * 33]); o.y = pkbf(s[2 * 33], s[3 * 33]); o.z = pkbf(s[4 * 33], s[5 * 33]); o.w = pkbf(s[6 * 33], s[7 * 33]);
;         *(u32x4*)(WT + (size_t)drow * K + k0 + 8 * c) = o;
;     }
;     asm volatile("s_waitcnt lgkmcnt(0)" ::: "memory");
; __device__ __forceinline__ void ph_wconv(CArgs& a, int l, unsigned char* ldsg, int gw, int ngw, int lane, int wv, int mask) {
;     ...
;     if (mask & 1) for (int it = gw; it < I_IN; it += ngw) transpose_item<1>(a.in[8] + (size_t)l * 1024 * 11680, 1024, 11680, (bf16_t*)(ws + WS_WIN), scr, it, lane);
	s_waitcnt lgkmcnt(0)
	v_or_b32_e32 v0, s40, v12
	ds_read2_b32 v[24:25], v13 offset0:33 offset1:41
	ds_read2_b32 v[26:27], v13 offset1:8
	ds_read2_b32 v[28:29], v13 offset0:66 offset1:74
	ds_read2_b32 v[30:31], v13 offset0:99 offset1:107
	ds_read2_b32 v[32:33], v13 offset0:132 offset1:140
	ds_read2_b32 v[34:35], v13 offset0:165 offset1:173
	ds_read2_b32 v[36:37], v13 offset0:198 offset1:206
	ds_read2_b32 v[38:39], v13 offset0:231 offset1:239
	v_cmp_lt_i32_e32 vcc, s9, v0
	v_add_u32_e32 v7, 0x60, v0
	s_ashr_i32 s43, s42, 31
	v_cndmask_b32_e32 v22, v0, v7, vcc
	v_ashrrev_i32_e32 v23, 31, v22
	v_lshl_add_u64 v[10:11], s[42:43], 1, v[8:9]
	v_lshlrev_b64 v[22:23], 11, v[22:23]
	v_or_b32_e32 v0, s40, v14
	s_waitcnt lgkmcnt(6)
	v_cvt_pk_bf16_f32 v18, v26, v24
	s_waitcnt lgkmcnt(4)
	v_cvt_pk_bf16_f32 v19, v28, v30
	s_waitcnt lgkmcnt(2)
	v_cvt_pk_bf16_f32 v20, v32, v34
	s_waitcnt lgkmcnt(0)
	v_cvt_pk_bf16_f32 v21, v36, v38
	v_lshl_add_u64 v[22:23], v[10:11], 0, v[22:23]
	v_cmp_lt_i32_e32 vcc, s9, v0
	v_add_u32_e32 v7, 0x60, v0
	global_store_dwordx4 v[22:23], v[18:21], off
	v_cndmask_b32_e32 v22, v0, v7, vcc
	v_ashrrev_i32_e32 v23, 31, v22
	v_lshlrev_b64 v[22:23], 11, v[22:23]
	v_cvt_pk_bf16_f32 v18, v27, v25
	v_cvt_pk_bf16_f32 v19, v29, v31
	v_cvt_pk_bf16_f32 v20, v33, v35
	v_cvt_pk_bf16_f32 v21, v37, v39
	v_lshl_add_u64 v[22:23], v[10:11], 0, v[22:23]
	global_store_dwordx4 v[22:23], v[18:21], off
	v_or_b32_e32 v0, s40, v15
	ds_read2_b32 v[24:25], v13 offset0:49 offset1:57
	ds_read2_b32 v[26:27], v13 offset0:16 offset1:24
	ds_read2_b32 v[28:29], v13 offset0:82 offset1:90
	ds_read2_b32 v[30:31], v13 offset0:115 offset1:123
	ds_read2_b32 v[32:33], v13 offset0:148 offset1:156
	ds_read2_b32 v[34:35], v13 offset0:181 offset1:189
	ds_read2_b32 v[36:37], v13 offset0:214 offset1:222
	ds_read2_b32 v[38:39], v13 offset0:247 offset1:255
	v_cmp_lt_i32_e32 vcc, s9, v0
	v_add_u32_e32 v7, 0x60, v0
	s_waitcnt lgkmcnt(6)
	v_cvt_pk_bf16_f32 v18, v26, v24
	v_cndmask_b32_e32 v22, v0, v7, vcc
	v_ashrrev_i32_e32 v23, 31, v22
	v_lshlrev_b64 v[22:23], 11, v[22:23]
	v_or_b32_e32 v0, s40, v16
	s_waitcnt lgkmcnt(4)
	v_cvt_pk_bf16_f32 v19, v28, v30
	s_waitcnt lgkmcnt(2)
	v_cvt_pk_bf16_f32 v20, v32, v34
	s_waitcnt lgkmcnt(0)
	v_cvt_pk_bf16_f32 v21, v36, v38
	v_lshl_add_u64 v[22:23], v[10:11], 0, v[22:23]
	v_cmp_lt_i32_e32 vcc, s9, v0
	v_add_u32_e32 v7, 0x60, v0
	global_store_dwordx4 v[22:23], v[18:21], off
	v_cndmask_b32_e32 v22, v0, v7, vcc
	v_ashrrev_i32_e32 v23, 31, v22
	v_lshlrev_b64 v[22:23], 11, v[22:23]
	v_cvt_pk_bf16_f32 v18, v27, v25
	v_cvt_pk_bf16_f32 v19, v29, v31
	v_cvt_pk_bf16_f32 v20, v33, v35
	v_cvt_pk_bf16_f32 v21, v37, v39
	v_lshl_add_u64 v[10:11], v[10:11], 0, v[22:23]
	global_store_dwordx4 v[10:11], v[18:21], off
	s_waitcnt lgkmcnt(0)
	s_add_i32 s1, s1, s80
	s_cmpk_lt_i32 s1, 0x16d0
	s_cbranch_scc1 .LBB0_233

; template <int MODE> __device__ __forceinline__ void transpose_item(const float* W, int K, int N, bf16_t* WT, LAS float* scr, int item, int lane) {
;     const int nblk = N / 32, kb = item / nblk, nb = item % nblk, k0 = 64 * kb, n0 = 32 * nb;
; #pragma unroll 8
;     for (int i = 0; i < 32; ++i) { const int kk = 2 * i + (lane >> 5); scr[kk * 33 + (lane & 31)] = W[(size_t)(k0 + kk) * N + n0 + (lane & 31)]; }
.LBB0_824:
	s_lshl_b32 s10, s5, 1
	s_lshl_b32 s7, s4, 1
	v_or_b32_e32 v20, s10, v0
	v_or_b32_e32 v18, s7, v7
	v_ashrrev_i32_e32 v21, 31, v20
	v_ashrrev_i32_e32 v19, 31, v18
	v_lshlrev_b64 v[20:21], 12, v[20:21]
	v_lshlrev_b64 v[18:19], 12, v[18:19]
	v_lshl_add_u64 v[20:21], v[10:11], 0, v[20:21]
	v_lshl_add_u64 v[18:19], v[10:11], 0, v[18:19]
	global_load_dword v44, v[20:21], off
	global_load_dword v45, v[18:19], off
	s_add_i32 s14, s10, 4
	s_add_i32 s11, s7, 4
	v_or_b32_e32 v20, s14, v0
	v_or_b32_e32 v18, s11, v7
	v_ashrrev_i32_e32 v21, 31, v20
	v_ashrrev_i32_e32 v19, 31, v18
	v_lshlrev_b64 v[20:21], 12, v[20:21]
	v_lshlrev_b64 v[18:19], 12, v[18:19]
	v_lshl_add_u64 v[20:21], v[10:11], 0, v[20:21]
	v_lshl_add_u64 v[18:19], v[10:11], 0, v[18:19]
	global_load_dword v46, v[20:21], off
	global_load_dword v47, v[18:19], off
	s_add_i32 s14, s10, 8
	s_add_i32 s11, s7, 8
	v_or_b32_e32 v20, s14, v0
	v_or_b32_e32 v18, s11, v7
	v_ashrrev_i32_e32 v21, 31, v20
	v_ashrrev_i32_e32 v19, 31, v18
	v_lshlrev_b64 v[20:21], 12, v[20:21]
	v_lshlrev_b64 v[18:19], 12, v[18:19]
	v_lshl_add_u64 v[20:21], v[10:11], 0, v[20:21]
	v_lshl_add_u64 v[18:19], v[10:11], 0, v[18:19]
	global_load_dword v48, v[20:21], off
	global_load_dword v49, v[18:19], off
	s_add_i32 s14, s10, 12
	s_add_i32 s11, s7, 12
	v_or_b32_e32 v20, s14, v0
	v_or_b32_e32 v18, s11, v7
	v_ashrrev_i32_e32 v21, 31, v20
	v_ashrrev_i32_e32 v19, 31, v18
	v_lshlrev_b64 v[20:21], 12, v[20:21]
	v_lshlrev_b64 v[18:19], 12, v[18:19]
	v_lshl_add_u64 v[20:21], v[10:11], 0, v[20:21]
	v_lshl_add_u64 v[18:19], v[10:11], 0, v[18:19]
	global_load_dword v50, v[20:21], off
	global_load_dword v51, v[18:19], off
	s_add_i32 s14, s10, 16
	s_add_i32 s11, s7, 16
	v_or_b32_e32 v20, s14, v0
	v_or_b32_e32 v18, s11, v7
	v_ashrrev_i32_e32 v21, 31, v20
	v_ashrrev_i32_e32 v19, 31, v18
	v_lshlrev_b64 v[20:21], 12, v[20:21]
	v_lshlrev_b64 v[18:19], 12, v[18:19]
	v_lshl_add_u64 v[20:21], v[10:11], 0, v[20:21]
	v_lshl_add_u64 v[18:19], v[10:11], 0, v[18:19]
	global_load_dword v52, v[20:21], off
	global_load_dword v53, v[18:19], off
	s_add_i32 s14, s10, 20
	s_add_i32 s11, s7, 20
	v_or_b32_e32 v20, s14, v0
	v_or_b32_e32 v18, s11, v7
	v_ashrrev_i32_e32 v21, 31, v20
	v_ashrrev_i32_e32 v19, 31, v18
	v_lshlrev_b64 v[20:21], 12, v[20:21]
	v_lshlrev_b64 v[18:19], 12, v[18:19]
	v_lshl_add_u64 v[20:21], v[10:11], 0, v[20:21]
	v_lshl_add_u64 v[18:19], v[10:11], 0, v[18:19]
	global_load_dword v54, v[20:21], off
	global_load_dword v55, v[18:19], off
	s_add_i32 s14, s10, 24
	s_add_i32 s11, s7, 24
	v_or_b32_e32 v20, s14, v0
	v_or_b32_e32 v18, s11, v7
	v_ashrrev_i32_e32 v21, 31, v20
	v_ashrrev_i32_e32 v19, 31, v18
	v_lshlrev_b64 v[20:21], 12, v[20:21]
	v_lshlrev_b64 v[18:19], 12, v[18:19]
	v_lshl_add_u64 v[20:21], v[10:11], 0, v[20:21]
	v_lshl_add_u64 v[18:19], v[10:11], 0, v[18:19]
	global_load_dword v56, v[20:21], off
	global_load_dword v57, v[18:19], off
	s_add_i32 s14, s10, 28
	s_add_i32 s11, s7, 28
	v_or_b32_e32 v20, s14, v0
	v_or_b32_e32 v18, s11, v7
	v_ashrrev_i32_e32 v21, 31, v20
	v_ashrrev_i32_e32 v19, 31, v18
	v_lshlrev_b64 v[20:21], 12, v[20:21]
	v_lshlrev_b64 v[18:19], 12, v[18:19]
	v_lshl_add_u64 v[20:21], v[10:11], 0, v[20:21]
	v_lshl_add_u64 v[18:19], v[10:11], 0, v[18:19]
	global_load_dword v58, v[20:21], off
	global_load_dword v59, v[18:19], off
	s_add_i32 s5, s5, 16
	s_add_i32 s4, s4, 16
	s_add_i32 s6, s6, -16
	v_or_b32_e32 v17, s7, v3
	v_or_b32_e32 v22, s10, v2
	v_mad_u64_u32 v[18:19], s[98:99], v22, s83, v[6:7]
	v_mad_u64_u32 v[20:21], s[98:99], v17, s83, v[6:7]
	s_waitcnt vmcnt(15)
	ds_write_b32 v18, v44
	s_waitcnt vmcnt(14)
	ds_write_b32 v20, v45
	s_add_i32 s14, s10, 4
	s_add_i32 s11, s7, 4
	v_or_b32_e32 v17, s11, v3
	v_or_b32_e32 v22, s14, v2
	v_mad_u64_u32 v[18:19], s[98:99], v22, s83, v[6:7]
	v_mad_u64_u32 v[20:21], s[98:99], v17, s83, v[6:7]
	s_waitcnt vmcnt(13)
	ds_write_b32 v18, v46
	s_waitcnt vmcnt(12)
	ds_write_b32 v20, v47
	s_add_i32 s14, s10, 8
	s_add_i32 s11, s7, 8
	v_or_b32_e32 v17, s11, v3
	v_or_b32_e32 v22, s14, v2
	v_mad_u64_u32 v[18:19], s[98:99], v22, s83, v[6:7]
	v_mad_u64_u32 v[20:21], s[98:99], v17, s83, v[6:7]
	s_waitcnt vmcnt(11)
	ds_write_b32 v18, v48
	s_waitcnt vmcnt(10)
	ds_write_b32 v20, v49
	s_add_i32 s14, s10, 12
	s_add_i32 s11, s7, 12
	v_or_b32_e32 v17, s11, v3
	v_or_b32_e32 v22, s14, v2
	v_mad_u64_u32 v[18:19], s[98:99], v22, s83, v[6:7]
	v_mad_u64_u32 v[20:21], s[98:99], v17, s83, v[6:7]
	s_waitcnt vmcnt(9)
	ds_write_b32 v18, v50
	s_waitcnt vmcnt(8)
	ds_write_b32 v20, v51
	s_add_i32 s14, s10, 16
	s_add_i32 s11, s7, 16
	v_or_b32_e32 v17, s11, v3
	v_or_b32_e32 v22, s14, v2
	v_mad_u64_u32 v[18:19], s[98:99], v22, s83, v[6:7]
	v_mad_u64_u32 v[20:21], s[98:99], v17, s83, v[6:7]
	s_waitcnt vmcnt(7)
	ds_write_b32 v18, v52
	s_waitcnt vmcnt(6)
	ds_write_b32 v20, v53
	s_add_i32 s14, s10, 20
	s_add_i32 s11, s7, 20
	v_or_b32_e32 v17, s11, v3
	v_or_b32_e32 v22, s14, v2
	v_mad_u64_u32 v[18:19], s[98:99], v22, s83, v[6:7]
	v_mad_u64_u32 v[20:21], s[98:99], v17, s83, v[6:7]
	s_waitcnt vmcnt(5)
	ds_write_b32 v18, v54
	s_waitcnt vmcnt(4)
	ds_write_b32 v20, v55
	s_add_i32 s14, s10, 24
	s_add_i32 s11, s7, 24
	v_or_b32_e32 v17, s11, v3
	v_or_b32_e32 v22, s14, v2
	v_mad_u64_u32 v[18:19], s[98:99], v22, s83, v[6:7]
	v_mad_u64_u32 v[20:21], s[98:99], v17, s83, v[6:7]
	s_waitcnt vmcnt(3)
	ds_write_b32 v18, v56
	s_waitcnt vmcnt(2)
	ds_write_b32 v20, v57
	s_add_i32 s14, s10, 28
	s_add_i32 s11, s7, 28
	v_or_b32_e32 v17, s11, v3
	v_or_b32_e32 v22, s14, v2
	v_mad_u64_u32 v[18:19], s[98:99], v22, s83, v[6:7]
	v_mad_u64_u32 v[20:21], s[98:99], v17, s83, v[6:7]
	s_waitcnt vmcnt(1)
	ds_write_b32 v18, v58
	s_waitcnt vmcnt(0)
	ds_write_b32 v20, v59
	s_cmp_lg_u32 s6, 0
	s_cbranch_scc1 .LBB0_824
; #define LAS __attribute__((address_space(3)))
; __device__ __forceinline__ unsigned pkbf(float lo, float hi) { f32x2 v = {lo, hi}; bf16x2v b = __builtin_convertvector(v, bf16x2v); return __builtin_bit_cast(unsigned, b); }
; template <int MODE> __device__ __forceinline__ void transpose_item(const float* W, int K, int N, bf16_t* WT, LAS float* scr, int item, int lane) {
;     ...
;     asm volatile("s_waitcnt lgkmcnt(0)" ::: "memory");
;     const int c = lane & 7;
; #pragma unroll
;     for (int j = 0; j < 4; ++j) {
;         const int n = (lane >> 3) + 8 * j, gn = n0 + n; const LAS float* s = scr + (8 * c) * 33 + n;
;         const int drow = MODE == 0 ? gn : (MODE == 1 ? (gn >= 8608 ? gn + 96 : gn) : (gn < DFF ? 2 * gn : 2 * (gn - DFF) + 1));
;         u32x4 o; o.x = pkbf(s[0 * 33], s[1 * 33]); o.y = pkbf(s[2 * 33], s[3 * 33]); o.z = pkbf(s[4 * 33], s[5 * 33]); o.w = pkbf(s[6 * 33], s[7 * 33]);
;         *(u32x4*)(WT + (size_t)drow * K + k0 + 8 * c) = o;
;     }
;     asm volatile("s_waitcnt lgkmcnt(0)" ::: "memory");
; __device__ __forceinline__ void ph_wconv(CArgs& a, int l, unsigned char* ldsg, int gw, int ngw, int lane, int wv, int mask) {
;     ...
;     if (mask & 4) for (int it = gw; it < I_SQ; it += ngw) transpose_item<0>(a.in[30] + (size_t)l * 1048576, 1024, 1024, (bf16_t*)(ws + WS_WO), scr, it, lane);
	s_waitcnt lgkmcnt(0)
	ds_read2_b32 v[24:25], v13 offset0:33 offset1:41
	ds_read2_b32 v[26:27], v13 offset1:8
	ds_read2_b32 v[28:29], v13 offset0:66 offset1:74
	ds_read2_b32 v[30:31], v13 offset0:99 offset1:107
	ds_read2_b32 v[32:33], v13 offset0:132 offset1:140
	ds_read2_b32 v[34:35], v13 offset0:165 offset1:173
	ds_read2_b32 v[36:37], v13 offset0:198 offset1:206
	ds_read2_b32 v[38:39], v13 offset0:231 offset1:239
	v_or_b32_e32 v22, s42, v12
	s_ashr_i32 s45, s44, 31
	v_ashrrev_i32_e32 v23, 31, v22
	v_lshl_add_u64 v[10:11], s[44:45], 1, v[8:9]
	v_lshlrev_b64 v[22:23], 11, v[22:23]
	s_waitcnt lgkmcnt(6)
	v_cvt_pk_bf16_f32 v18, v26, v24
	s_waitcnt lgkmcnt(4)
	v_cvt_pk_bf16_f32 v19, v28, v30
	s_waitcnt lgkmcnt(2)
	v_cvt_pk_bf16_f32 v20, v32, v34
	s_waitcnt lgkmcnt(0)
	v_cvt_pk_bf16_f32 v21, v36, v38
	v_lshl_add_u64 v[22:23], v[10:11], 0, v[22:23]
	global_store_dwordx4 v[22:23], v[18:21], off
	v_or_b32_e32 v22, s42, v14
	v_ashrrev_i32_e32 v23, 31, v22
	v_lshlrev_b64 v[22:23], 11, v[22:23]
	v_cvt_pk_bf16_f32 v18, v27, v25
	v_cvt_pk_bf16_f32 v19, v29, v31
	v_cvt_pk_bf16_f32 v20, v33, v35
	v_cvt_pk_bf16_f32 v21, v37, v39
	v_lshl_add_u64 v[22:23], v[10:11], 0, v[22:23]
	global_store_dwordx4 v[22:23], v[18:21], off
	ds_read2_b32 v[24:25], v13 offset0:49 offset1:57
	ds_read2_b32 v[26:27], v13 offset0:16 offset1:24
	ds_read2_b32 v[28:29], v13 offset0:82 offset1:90
	ds_read2_b32 v[30:31], v13 offset0:115 offset1:123
	ds_read2_b32 v[32:33], v13 offset0:148 offset1:156
	ds_read2_b32 v[34:35], v13 offset0:181 offset1:189
	ds_read2_b32 v[36:37], v13 offset0:214 offset1:222
	ds_read2_b32 v[38:39], v13 offset0:247 offset1:255
	v_or_b32_e32 v22, s42, v15
	v_ashrrev_i32_e32 v23, 31, v22
	v_lshlrev_b64 v[22:23], 11, v[22:23]
	s_waitcnt lgkmcnt(6)
	v_cvt_pk_bf16_f32 v18, v26, v24
	s_waitcnt lgkmcnt(4)
	v_cvt_pk_bf16_f32 v19, v28, v30
	s_waitcnt lgkmcnt(2)
	v_cvt_pk_bf16_f32 v20, v32, v34
	s_waitcnt lgkmcnt(0)
	v_cvt_pk_bf16_f32 v21, v36, v38
	v_lshl_add_u64 v[22:23], v[10:11], 0, v[22:23]
	global_store_dwordx4 v[22:23], v[18:21], off
	v_or_b32_e32 v22, s42, v16
	v_ashrrev_i32_e32 v23, 31, v22
	v_lshlrev_b64 v[22:23], 11, v[22:23]
	v_cvt_pk_bf16_f32 v18, v27, v25
	v_cvt_pk_bf16_f32 v19, v29, v31
	v_cvt_pk_bf16_f32 v20, v33, v35
	v_cvt_pk_bf16_f32 v21, v37, v39
	v_lshl_add_u64 v[10:11], v[10:11], 0, v[22:23]
	global_store_dwordx4 v[10:11], v[18:21], off
	s_waitcnt lgkmcnt(0)
	s_add_i32 s3, s3, s80
	s_cmpk_lt_i32 s3, 0x200
	s_cbranch_scc1 .LBB0_823

; template <int MODE> __device__ __forceinline__ void transpose_item(const float* W, int K, int N, bf16_t* WT, LAS float* scr, int item, int lane) {
;     const int nblk = N / 32, kb = item / nblk, nb = item % nblk, k0 = 64 * kb, n0 = 32 * nb;
; #pragma unroll 8
;     for (int i = 0; i < 32; ++i) { const int kk = 2 * i + (lane >> 5); scr[kk * 33 + (lane & 31)] = W[(size_t)(k0 + kk) * N + n0 + (lane & 31)]; }
.LBB0_829:
	s_lshl_b32 s7, s4, 1
	s_lshl_b32 s6, s3, 1
	v_or_b32_e32 v18, s7, v0
	v_or_b32_e32 v20, s6, v7
	v_mad_i64_i32 v[18:19], s[98:99], v18, s31, v[10:11]
	v_mad_i64_i32 v[20:21], s[98:99], v20, s31, v[10:11]
	global_load_dword v44, v[18:19], off
	global_load_dword v45, v[20:21], off
	s_add_i32 s11, s7, 4
	s_add_i32 s10, s6, 4
	v_or_b32_e32 v18, s11, v0
	v_or_b32_e32 v20, s10, v7
	v_mad_i64_i32 v[18:19], s[98:99], v18, s31, v[10:11]
	v_mad_i64_i32 v[20:21], s[98:99], v20, s31, v[10:11]
	global_load_dword v46, v[18:19], off
	global_load_dword v47, v[20:21], off
	s_add_i32 s11, s7, 8
	s_add_i32 s10, s6, 8
	v_or_b32_e32 v18, s11, v0
	v_or_b32_e32 v20, s10, v7
	v_mad_i64_i32 v[18:19], s[98:99], v18, s31, v[10:11]
	v_mad_i64_i32 v[20:21], s[98:99], v20, s31, v[10:11]
	global_load_dword v48, v[18:19], off
	global_load_dword v49, v[20:21], off
	s_add_i32 s11, s7, 12
	s_add_i32 s10, s6, 12
	v_or_b32_e32 v18, s11, v0
	v_or_b32_e32 v20, s10, v7
	v_mad_i64_i32 v[18:19], s[98:99], v18, s31, v[10:11]
	v_mad_i64_i32 v[20:21], s[98:99], v20, s31, v[10:11]
	global_load_dword v50, v[18:19], off
	global_load_dword v51, v[20:21], off
	s_add_i32 s11, s7, 16
	s_add_i32 s10, s6, 16
	v_or_b32_e32 v18, s11, v0
	v_or_b32_e32 v20, s10, v7
	v_mad_i64_i32 v[18:19], s[98:99], v18, s31, v[10:11]
	v_mad_i64_i32 v[20:21], s[98:99], v20, s31, v[10:11]
	global_load_dword v52, v[18:19], off
	global_load_dword v53, v[20:21], off
	s_add_i32 s11, s7, 20
	s_add_i32 s10, s6, 20
	v_or_b32_e32 v18, s11, v0
	v_or_b32_e32 v20, s10, v7
	v_mad_i64_i32 v[18:19], s[98:99], v18, s31, v[10:11]
	v_mad_i64_i32 v[20:21], s[98:99], v20, s31, v[10:11]
	global_load_dword v54, v[18:19], off
	global_load_dword v55, v[20:21], off
	s_add_i32 s11, s7, 24
	s_add_i32 s10, s6, 24
	v_or_b32_e32 v18, s11, v0
	v_or_b32_e32 v20, s10, v7
	v_mad_i64_i32 v[18:19], s[98:99], v18, s31, v[10:11]
	v_mad_i64_i32 v[20:21], s[98:99], v20, s31, v[10:11]
	global_load_dword v56, v[18:19], off
	global_load_dword v57, v[20:21], off
	s_add_i32 s11, s7, 28
	s_add_i32 s10, s6, 28
	v_or_b32_e32 v18, s11, v0
	v_or_b32_e32 v20, s10, v7
	v_mad_i64_i32 v[18:19], s[98:99], v18, s31, v[10:11]
	v_mad_i64_i32 v[20:21], s[98:99], v20, s31, v[10:11]
	global_load_dword v58, v[18:19], off
	global_load_dword v59, v[20:21], off
	s_add_i32 s4, s4, 16
	s_add_i32 s3, s3, 16
	s_add_i32 s5, s5, -16
	v_or_b32_e32 v17, s6, v3
	v_or_b32_e32 v22, s7, v2
	v_mad_u64_u32 v[18:19], s[98:99], v22, s83, v[6:7]
	v_mad_u64_u32 v[20:21], s[98:99], v17, s83, v[6:7]
	s_waitcnt vmcnt(15)
	ds_write_b32 v18, v44
	s_waitcnt vmcnt(14)
	ds_write_b32 v20, v45
	s_add_i32 s11, s7, 4
	s_add_i32 s10, s6, 4
	v_or_b32_e32 v17, s10, v3
	v_or_b32_e32 v22, s11, v2
	v_mad_u64_u32 v[18:19], s[98:99], v22, s83, v[6:7]
	v_mad_u64_u32 v[20:21], s[98:99], v17, s83, v[6:7]
	s_waitcnt vmcnt(13)
	ds_write_b32 v18, v46
	s_waitcnt vmcnt(12)
	ds_write_b32 v20, v47
	s_add_i32 s11, s7, 8
	s_add_i32 s10, s6, 8
	v_or_b32_e32 v17, s10, v3
	v_or_b32_e32 v22, s11, v2
	v_mad_u64_u32 v[18:19], s[98:99], v22, s83, v[6:7]
	v_mad_u64_u32 v[20:21], s[98:99], v17, s83, v[6:7]
	s_waitcnt vmcnt(11)
	ds_write_b32 v18, v48
	s_waitcnt vmcnt(10)
	ds_write_b32 v20, v49
	s_add_i32 s11, s7, 12
	s_add_i32 s10, s6, 12
	v_or_b32_e32 v17, s10, v3
	v_or_b32_e32 v22, s11, v2
	v_mad_u64_u32 v[18:19], s[98:99], v22, s83, v[6:7]
	v_mad_u64_u32 v[20:21], s[98:99], v17, s83, v[6:7]
	s_waitcnt vmcnt(9)
	ds_write_b32 v18, v50
	s_waitcnt vmcnt(8)
	ds_write_b32 v20, v51
	s_add_i32 s11, s7, 16
	s_add_i32 s10, s6, 16
	v_or_b32_e32 v17, s10, v3
	v_or_b32_e32 v22, s11, v2
	v_mad_u64_u32 v[18:19], s[98:99], v22, s83, v[6:7]
	v_mad_u64_u32 v[20:21], s[98:99], v17, s83, v[6:7]
	s_waitcnt vmcnt(7)
	ds_write_b32 v18, v52
	s_waitcnt vmcnt(6)
	ds_write_b32 v20, v53
	s_add_i32 s11, s7, 20
	s_add_i32 s10, s6, 20
	v_or_b32_e32 v17, s10, v3
	v_or_b32_e32 v22, s11, v2
	v_mad_u64_u32 v[18:19], s[98:99], v22, s83, v[6:7]
	v_mad_u64_u32 v[20:21], s[98:99], v17, s83, v[6:7]
	s_waitcnt vmcnt(5)
	ds_write_b32 v18, v54
	s_waitcnt vmcnt(4)
	ds_write_b32 v20, v55
	s_add_i32 s11, s7, 24
	s_add_i32 s10, s6, 24
	v_or_b32_e32 v17, s10, v3
	v_or_b32_e32 v22, s11, v2
	v_mad_u64_u32 v[18:19], s[98:99], v22, s83, v[6:7]
	v_mad_u64_u32 v[20:21], s[98:99], v17, s83, v[6:7]
	s_waitcnt vmcnt(3)
	ds_write_b32 v18, v56
	s_waitcnt vmcnt(2)
	ds_write_b32 v20, v57
	s_add_i32 s11, s7, 28
	s_add_i32 s10, s6, 28
	v_or_b32_e32 v17, s10, v3
	v_or_b32_e32 v22, s11, v2
	v_mad_u64_u32 v[18:19], s[98:99], v22, s83, v[6:7]
	v_mad_u64_u32 v[20:21], s[98:99], v17, s83, v[6:7]
	s_waitcnt vmcnt(1)
	ds_write_b32 v18, v58
	s_waitcnt vmcnt(0)
	ds_write_b32 v20, v59
	s_cmp_lg_u32 s5, 0
	s_cbranch_scc1 .LBB0_829
; #define LAS __attribute__((address_space(3)))
; __device__ __forceinline__ unsigned pkbf(float lo, float hi) { f32x2 v = {lo, hi}; bf16x2v b = __builtin_convertvector(v, bf16x2v); return __builtin_bit_cast(unsigned, b); }
; template <int MODE> __device__ __forceinline__ void transpose_item(const float* W, int K, int N, bf16_t* WT, LAS float* scr, int item, int lane) {
;     ...
;     asm volatile("s_waitcnt lgkmcnt(0)" ::: "memory");
;     const int c = lane & 7;
; #pragma unroll
;     for (int j = 0; j < 4; ++j) {
;         const int n = (lane >> 3) + 8 * j, gn = n0 + n; const LAS float* s = scr + (8 * c) * 33 + n;
;         const int drow = MODE == 0 ? gn : (MODE == 1 ? (gn >= 8608 ? gn + 96 : gn) : (gn < DFF ? 2 * gn : 2 * (gn - DFF) + 1));
;         u32x4 o; o.x = pkbf(s[0 * 33], s[1 * 33]); o.y = pkbf(s[2 * 33], s[3 * 33]); o.z = pkbf(s[4 * 33], s[5 * 33]); o.w = pkbf(s[6 * 33], s[7 * 33]);
;         *(u32x4*)(WT + (size_t)drow * K + k0 + 8 * c) = o;
;     }
;     asm volatile("s_waitcnt lgkmcnt(0)" ::: "memory");
; __device__ __forceinline__ void ph_wconv(CArgs& a, int l, unsigned char* ldsg, int gw, int ngw, int lane, int wv, int mask) {
;     ...
;     if (mask & 8) for (int it = gw; it < I_WI; it += ngw) transpose_item<2>(a.in[31] + (size_t)l * 1024 * 5632, 1024, 5632, (bf16_t*)(ws + WS_WI), scr, it, lane);
	s_waitcnt lgkmcnt(0)
	v_or_b32_e32 v0, s40, v12
	v_cmp_gt_i32_e32 vcc, s30, v0
	v_lshlrev_b32_e32 v0, 1, v0
	ds_read2_b32 v[24:25], v13 offset0:33 offset1:41
	ds_read2_b32 v[26:27], v13 offset1:8
	ds_read2_b32 v[28:29], v13 offset0:66 offset1:74
	ds_read2_b32 v[30:31], v13 offset0:99 offset1:107
	ds_read2_b32 v[32:33], v13 offset0:132 offset1:140
	ds_read2_b32 v[34:35], v13 offset0:165 offset1:173
	ds_read2_b32 v[36:37], v13 offset0:198 offset1:206
	ds_read2_b32 v[38:39], v13 offset0:231 offset1:239
	v_add_u32_e32 v7, 0xffffea01, v0
	v_cndmask_b32_e32 v22, v7, v0, vcc
	s_ashr_i32 s43, s42, 31
	v_ashrrev_i32_e32 v23, 31, v22
	v_or_b32_e32 v0, s40, v14
	v_lshl_add_u64 v[10:11], s[42:43], 1, v[8:9]
	v_lshlrev_b64 v[22:23], 11, v[22:23]
	v_cmp_gt_i32_e32 vcc, s30, v0
	v_lshlrev_b32_e32 v0, 1, v0
	s_waitcnt lgkmcnt(6)
	v_cvt_pk_bf16_f32 v18, v26, v24
	s_waitcnt lgkmcnt(4)
	v_cvt_pk_bf16_f32 v19, v28, v30
	s_waitcnt lgkmcnt(2)
	v_cvt_pk_bf16_f32 v20, v32, v34
	s_waitcnt lgkmcnt(0)
	v_cvt_pk_bf16_f32 v21, v36, v38
	v_lshl_add_u64 v[22:23], v[10:11], 0, v[22:23]
	v_add_u32_e32 v7, 0xffffea01, v0
	global_store_dwordx4 v[22:23], v[18:21], off
	v_cndmask_b32_e32 v22, v7, v0, vcc
	v_ashrrev_i32_e32 v23, 31, v22
	v_lshlrev_b64 v[22:23], 11, v[22:23]
	v_cvt_pk_bf16_f32 v18, v27, v25
	v_cvt_pk_bf16_f32 v19, v29, v31
	v_cvt_pk_bf16_f32 v20, v33, v35
	v_cvt_pk_bf16_f32 v21, v37, v39
	v_lshl_add_u64 v[22:23], v[10:11], 0, v[22:23]
	global_store_dwordx4 v[22:23], v[18:21], off
	v_or_b32_e32 v0, s40, v15
	v_cmp_gt_i32_e32 vcc, s30, v0
	v_lshlrev_b32_e32 v0, 1, v0
	ds_read2_b32 v[24:25], v13 offset0:49 offset1:57
	ds_read2_b32 v[26:27], v13 offset0:16 offset1:24
	ds_read2_b32 v[28:29], v13 offset0:82 offset1:90
	ds_read2_b32 v[30:31], v13 offset0:115 offset1:123
	ds_read2_b32 v[32:33], v13 offset0:148 offset1:156
	ds_read2_b32 v[34:35], v13 offset0:181 offset1:189
	ds_read2_b32 v[36:37], v13 offset0:214 offset1:222
	ds_read2_b32 v[38:39], v13 offset0:247 offset1:255
	v_add_u32_e32 v7, 0xffffea01, v0
	v_cndmask_b32_e32 v22, v7, v0, vcc
	v_ashrrev_i32_e32 v23, 31, v22
	v_or_b32_e32 v0, s40, v16
	v_lshlrev_b64 v[22:23], 11, v[22:23]
	v_cmp_gt_i32_e32 vcc, s30, v0
	v_lshlrev_b32_e32 v0, 1, v0
	s_waitcnt lgkmcnt(6)
	v_cvt_pk_bf16_f32 v18, v26, v24
	s_waitcnt lgkmcnt(4)
	v_cvt_pk_bf16_f32 v19, v28, v30
	s_waitcnt lgkmcnt(2)
	v_cvt_pk_bf16_f32 v20, v32, v34
	s_waitcnt lgkmcnt(0)
	v_cvt_pk_bf16_f32 v21, v36, v38
	v_lshl_add_u64 v[22:23], v[10:11], 0, v[22:23]
	v_add_u32_e32 v7, 0xffffea01, v0
	global_store_dwordx4 v[22:23], v[18:21], off
	v_cndmask_b32_e32 v22, v7, v0, vcc
	v_ashrrev_i32_e32 v23, 31, v22
	v_lshlrev_b64 v[22:23], 11, v[22:23]
	v_cvt_pk_bf16_f32 v18, v27, v25
	v_cvt_pk_bf16_f32 v19, v29, v31
	v_cvt_pk_bf16_f32 v20, v33, v35
	v_cvt_pk_bf16_f32 v21, v37, v39
	v_lshl_add_u64 v[10:11], v[10:11], 0, v[22:23]
	global_store_dwordx4 v[10:11], v[18:21], off
	s_waitcnt lgkmcnt(0)
	s_add_i32 s1, s1, s80
	s_cmpk_gt_i32 s1, 0xaff
	s_cbranch_scc0 .LBB0_828

; template <int MODE> __device__ __forceinline__ void transpose_item(const float* W, int K, int N, bf16_t* WT, LAS float* scr, int item, int lane) {
;     const int nblk = N / 32, kb = item / nblk, nb = item % nblk, k0 = 64 * kb, n0 = 32 * nb;
; #pragma unroll 8
;     for (int i = 0; i < 32; ++i) { const int kk = 2 * i + (lane >> 5); scr[kk * 33 + (lane & 31)] = W[(size_t)(k0 + kk) * N + n0 + (lane & 31)]; }
.LBB0_836:
	s_lshl_b32 s14, s7, 1
	s_lshl_b32 s11, s6, 1
	v_or_b32_e32 v20, s14, v0
	v_or_b32_e32 v18, s11, v7
	v_ashrrev_i32_e32 v21, 31, v20
	v_ashrrev_i32_e32 v19, 31, v18
	v_lshlrev_b64 v[20:21], 12, v[20:21]
	v_lshlrev_b64 v[18:19], 12, v[18:19]
	v_lshl_add_u64 v[20:21], v[10:11], 0, v[20:21]
	v_lshl_add_u64 v[18:19], v[10:11], 0, v[18:19]
	global_load_dword v44, v[20:21], off
	global_load_dword v45, v[18:19], off
	s_add_i32 s17, s14, 4
	s_add_i32 s16, s11, 4
	v_or_b32_e32 v20, s17, v0
	v_or_b32_e32 v18, s16, v7
	v_ashrrev_i32_e32 v21, 31, v20
	v_ashrrev_i32_e32 v19, 31, v18
	v_lshlrev_b64 v[20:21], 12, v[20:21]
	v_lshlrev_b64 v[18:19], 12, v[18:19]
	v_lshl_add_u64 v[20:21], v[10:11], 0, v[20:21]
	v_lshl_add_u64 v[18:19], v[10:11], 0, v[18:19]
	global_load_dword v46, v[20:21], off
	global_load_dword v47, v[18:19], off
	s_add_i32 s17, s14, 8
	s_add_i32 s16, s11, 8
	v_or_b32_e32 v20, s17, v0
	v_or_b32_e32 v18, s16, v7
	v_ashrrev_i32_e32 v21, 31, v20
	v_ashrrev_i32_e32 v19, 31, v18
	v_lshlrev_b64 v[20:21], 12, v[20:21]
	v_lshlrev_b64 v[18:19], 12, v[18:19]
	v_lshl_add_u64 v[20:21], v[10:11], 0, v[20:21]
	v_lshl_add_u64 v[18:19], v[10:11], 0, v[18:19]
	global_load_dword v48, v[20:21], off
	global_load_dword v49, v[18:19], off
	s_add_i32 s17, s14, 12
	s_add_i32 s16, s11, 12
	v_or_b32_e32 v20, s17, v0
	v_or_b32_e32 v18, s16, v7
	v_ashrrev_i32_e32 v21, 31, v20
	v_ashrrev_i32_e32 v19, 31, v18
	v_lshlrev_b64 v[20:21], 12, v[20:21]
	v_lshlrev_b64 v[18:19], 12, v[18:19]
	v_lshl_add_u64 v[20:21], v[10:11], 0, v[20:21]
	v_lshl_add_u64 v[18:19], v[10:11], 0, v[18:19]
	global_load_dword v50, v[20:21], off
	global_load_dword v51, v[18:19], off
	s_add_i32 s17, s14, 16
	s_add_i32 s16, s11, 16
	v_or_b32_e32 v20, s17, v0
	v_or_b32_e32 v18, s16, v7
	v_ashrrev_i32_e32 v21, 31, v20
	v_ashrrev_i32_e32 v19, 31, v18
	v_lshlrev_b64 v[20:21], 12, v[20:21]
	v_lshlrev_b64 v[18:19], 12, v[18:19]
	v_lshl_add_u64 v[20:21], v[10:11], 0, v[20:21]
	v_lshl_add_u64 v[18:19], v[10:11], 0, v[18:19]
	global_load_dword v52, v[20:21], off
	global_load_dword v53, v[18:19], off
	s_add_i32 s17, s14, 20
	s_add_i32 s16, s11, 20
	v_or_b32_e32 v20, s17, v0
	v_or_b32_e32 v18, s16, v7
	v_ashrrev_i32_e32 v21, 31, v20
	v_ashrrev_i32_e32 v19, 31, v18
	v_lshlrev_b64 v[20:21], 12, v[20:21]
	v_lshlrev_b64 v[18:19], 12, v[18:19]
	v_lshl_add_u64 v[20:21], v[10:11], 0, v[20:21]
	v_lshl_add_u64 v[18:19], v[10:11], 0, v[18:19]
	global_load_dword v54, v[20:21], off
	global_load_dword v55, v[18:19], off
	s_add_i32 s17, s14, 24
	s_add_i32 s16, s11, 24
	v_or_b32_e32 v20, s17, v0
	v_or_b32_e32 v18, s16, v7
	v_ashrrev_i32_e32 v21, 31, v20
	v_ashrrev_i32_e32 v19, 31, v18
	v_lshlrev_b64 v[20:21], 12, v[20:21]
	v_lshlrev_b64 v[18:19], 12, v[18:19]
	v_lshl_add_u64 v[20:21], v[10:11], 0, v[20:21]
	v_lshl_add_u64 v[18:19], v[10:11], 0, v[18:19]
	global_load_dword v56, v[20:21], off
	global_load_dword v57, v[18:19], off
	s_add_i32 s17, s14, 28
	s_add_i32 s16, s11, 28
	v_or_b32_e32 v20, s17, v0
	v_or_b32_e32 v18, s16, v7
	v_ashrrev_i32_e32 v21, 31, v20
	v_ashrrev_i32_e32 v19, 31, v18
	v_lshlrev_b64 v[20:21], 12, v[20:21]
	v_lshlrev_b64 v[18:19], 12, v[18:19]
	v_lshl_add_u64 v[20:21], v[10:11], 0, v[20:21]
	v_lshl_add_u64 v[18:19], v[10:11], 0, v[18:19]
	global_load_dword v58, v[20:21], off
	global_load_dword v59, v[18:19], off
	s_add_i32 s7, s7, 16
	s_add_i32 s6, s6, 16
	s_add_i32 s10, s10, -16
	v_or_b32_e32 v17, s11, v3
	v_or_b32_e32 v22, s14, v2
	v_mad_u64_u32 v[18:19], s[98:99], v22, s83, v[6:7]
	v_mad_u64_u32 v[20:21], s[98:99], v17, s83, v[6:7]
	s_waitcnt vmcnt(15)
	ds_write_b32 v18, v44
	s_waitcnt vmcnt(14)
	ds_write_b32 v20, v45
	s_add_i32 s17, s14, 4
	s_add_i32 s16, s11, 4
	v_or_b32_e32 v17, s16, v3
	v_or_b32_e32 v22, s17, v2
	v_mad_u64_u32 v[18:19], s[98:99], v22, s83, v[6:7]
	v_mad_u64_u32 v[20:21], s[98:99], v17, s83, v[6:7]
	s_waitcnt vmcnt(13)
	ds_write_b32 v18, v46
	s_waitcnt vmcnt(12)
	ds_write_b32 v20, v47
	s_add_i32 s17, s14, 8
	s_add_i32 s16, s11, 8
	v_or_b32_e32 v17, s16, v3
	v_or_b32_e32 v22, s17, v2
	v_mad_u64_u32 v[18:19], s[98:99], v22, s83, v[6:7]
	v_mad_u64_u32 v[20:21], s[98:99], v17, s83, v[6:7]
	s_waitcnt vmcnt(11)
	ds_write_b32 v18, v48
	s_waitcnt vmcnt(10)
	ds_write_b32 v20, v49
	s_add_i32 s17, s14, 12
	s_add_i32 s16, s11, 12
	v_or_b32_e32 v17, s16, v3
	v_or_b32_e32 v22, s17, v2
	v_mad_u64_u32 v[18:19], s[98:99], v22, s83, v[6:7]
	v_mad_u64_u32 v[20:21], s[98:99], v17, s83, v[6:7]
	s_waitcnt vmcnt(9)
	ds_write_b32 v18, v50
	s_waitcnt vmcnt(8)
	ds_write_b32 v20, v51
	s_add_i32 s17, s14, 16
	s_add_i32 s16, s11, 16
	v_or_b32_e32 v17, s16, v3
	v_or_b32_e32 v22, s17, v2
	v_mad_u64_u32 v[18:19], s[98:99], v22, s83, v[6:7]
	v_mad_u64_u32 v[20:21], s[98:99], v17, s83, v[6:7]
	s_waitcnt vmcnt(7)
	ds_write_b32 v18, v52
	s_waitcnt vmcnt(6)
	ds_write_b32 v20, v53
	s_add_i32 s17, s14, 20
	s_add_i32 s16, s11, 20
	v_or_b32_e32 v17, s16, v3
	v_or_b32_e32 v22, s17, v2
	v_mad_u64_u32 v[18:19], s[98:99], v22, s83, v[6:7]
	v_mad_u64_u32 v[20:21], s[98:99], v17, s83, v[6:7]
	s_waitcnt vmcnt(5)
	ds_write_b32 v18, v54
	s_waitcnt vmcnt(4)
	ds_write_b32 v20, v55
	s_add_i32 s17, s14, 24
	s_add_i32 s16, s11, 24
	v_or_b32_e32 v17, s16, v3
	v_or_b32_e32 v22, s17, v2
	v_mad_u64_u32 v[18:19], s[98:99], v22, s83, v[6:7]
	v_mad_u64_u32 v[20:21], s[98:99], v17, s83, v[6:7]
	s_waitcnt vmcnt(3)
	ds_write_b32 v18, v56
	s_waitcnt vmcnt(2)
	ds_write_b32 v20, v57
	s_add_i32 s17, s14, 28
	s_add_i32 s16, s11, 28
	v_or_b32_e32 v17, s16, v3
	v_or_b32_e32 v22, s17, v2
	v_mad_u64_u32 v[18:19], s[98:99], v22, s83, v[6:7]
	v_mad_u64_u32 v[20:21], s[98:99], v17, s83, v[6:7]
	s_waitcnt vmcnt(1)
	ds_write_b32 v18, v58
	s_waitcnt vmcnt(0)
	ds_write_b32 v20, v59
	s_cmp_lg_u32 s10, 0
	s_cbranch_scc1 .LBB0_836
; #define LAS __attribute__((address_space(3)))
; __device__ __forceinline__ unsigned pkbf(float lo, float hi) { f32x2 v = {lo, hi}; bf16x2v b = __builtin_convertvector(v, bf16x2v); return __builtin_bit_cast(unsigned, b); }
; template <int MODE> __device__ __forceinline__ void transpose_item(const float* W, int K, int N, bf16_t* WT, LAS float* scr, int item, int lane) {
;     ...
;     asm volatile("s_waitcnt lgkmcnt(0)" ::: "memory");
;     const int c = lane & 7;
; #pragma unroll
;     for (int j = 0; j < 4; ++j) {
;         const int n = (lane >> 3) + 8 * j, gn = n0 + n; const LAS float* s = scr + (8 * c) * 33 + n;
;         const int drow = MODE == 0 ? gn : (MODE == 1 ? (gn >= 8608 ? gn + 96 : gn) : (gn < DFF ? 2 * gn : 2 * (gn - DFF) + 1));
;         u32x4 o; o.x = pkbf(s[0 * 33], s[1 * 33]); o.y = pkbf(s[2 * 33], s[3 * 33]); o.z = pkbf(s[4 * 33], s[5 * 33]); o.w = pkbf(s[6 * 33], s[7 * 33]);
;         *(u32x4*)(WT + (size_t)drow * K + k0 + 8 * c) = o;
;     }
;     asm volatile("s_waitcnt lgkmcnt(0)" ::: "memory");
; __device__ __forceinline__ void ph_wconv(CArgs& a, int l, unsigned char* ldsg, int gw, int ngw, int lane, int wv, int mask) {
;     ...
;     if (mask & 4) for (int it = gw; it < I_SQ; it += ngw) transpose_item<0>(a.in[30] + (size_t)l * 1048576, 1024, 1024, (bf16_t*)(ws + WS_WO), scr, it, lane);
	s_waitcnt lgkmcnt(0)
	ds_read2_b32 v[24:25], v13 offset0:33 offset1:41
	ds_read2_b32 v[26:27], v13 offset1:8
	ds_read2_b32 v[28:29], v13 offset0:66 offset1:74
	ds_read2_b32 v[30:31], v13 offset0:99 offset1:107
	ds_read2_b32 v[32:33], v13 offset0:132 offset1:140
	ds_read2_b32 v[34:35], v13 offset0:165 offset1:173
	ds_read2_b32 v[36:37], v13 offset0:198 offset1:206
	ds_read2_b32 v[38:39], v13 offset0:231 offset1:239
	v_or_b32_e32 v22, s42, v12
	s_ashr_i32 s45, s44, 31
	v_ashrrev_i32_e32 v23, 31, v22
	v_lshl_add_u64 v[10:11], s[44:45], 1, v[8:9]
	v_lshlrev_b64 v[22:23], 11, v[22:23]
	s_waitcnt lgkmcnt(6)
	v_cvt_pk_bf16_f32 v18, v26, v24
	s_waitcnt lgkmcnt(4)
	v_cvt_pk_bf16_f32 v19, v28, v30
	s_waitcnt lgkmcnt(2)
	v_cvt_pk_bf16_f32 v20, v32, v34
	s_waitcnt lgkmcnt(0)
	v_cvt_pk_bf16_f32 v21, v36, v38
	v_lshl_add_u64 v[22:23], v[10:11], 0, v[22:23]
	global_store_dwordx4 v[22:23], v[18:21], off
	v_or_b32_e32 v22, s42, v14
	v_ashrrev_i32_e32 v23, 31, v22
	v_lshlrev_b64 v[22:23], 11, v[22:23]
	v_cvt_pk_bf16_f32 v18, v27, v25
	v_cvt_pk_bf16_f32 v19, v29, v31
	v_cvt_pk_bf16_f32 v20, v33, v35
	v_cvt_pk_bf16_f32 v21, v37, v39
	v_lshl_add_u64 v[22:23], v[10:11], 0, v[22:23]
	global_store_dwordx4 v[22:23], v[18:21], off
	ds_read2_b32 v[24:25], v13 offset0:49 offset1:57
	ds_read2_b32 v[26:27], v13 offset0:16 offset1:24
	ds_read2_b32 v[28:29], v13 offset0:82 offset1:90
	ds_read2_b32 v[30:31], v13 offset0:115 offset1:123
	ds_read2_b32 v[32:33], v13 offset0:148 offset1:156
	ds_read2_b32 v[34:35], v13 offset0:181 offset1:189
	ds_read2_b32 v[36:37], v13 offset0:214 offset1:222
	ds_read2_b32 v[38:39], v13 offset0:247 offset1:255
	v_or_b32_e32 v22, s42, v15
	v_ashrrev_i32_e32 v23, 31, v22
	v_lshlrev_b64 v[22:23], 11, v[22:23]
	s_waitcnt lgkmcnt(6)
	v_cvt_pk_bf16_f32 v18, v26, v24
	s_waitcnt lgkmcnt(4)
	v_cvt_pk_bf16_f32 v19, v28, v30
	s_waitcnt lgkmcnt(2)
	v_cvt_pk_bf16_f32 v20, v32, v34
	s_waitcnt lgkmcnt(0)
	v_cvt_pk_bf16_f32 v21, v36, v38
	v_lshl_add_u64 v[22:23], v[10:11], 0, v[22:23]
	global_store_dwordx4 v[22:23], v[18:21], off
	v_or_b32_e32 v22, s42, v16
	v_ashrrev_i32_e32 v23, 31, v22
	v_lshlrev_b64 v[22:23], 11, v[22:23]
	v_cvt_pk_bf16_f32 v18, v27, v25
	v_cvt_pk_bf16_f32 v19, v29, v31
	v_cvt_pk_bf16_f32 v20, v33, v35
	v_cvt_pk_bf16_f32 v21, v37, v39
	v_lshl_add_u64 v[10:11], v[10:11], 0, v[22:23]
	global_store_dwordx4 v[10:11], v[18:21], off
	s_waitcnt lgkmcnt(0)
	s_add_i32 s5, s5, s3
	s_cmpk_lt_i32 s5, 0x200
	s_cbranch_scc1 .LBB0_835

; template <int MODE> __device__ __forceinline__ void transpose_item(const float* W, int K, int N, bf16_t* WT, LAS float* scr, int item, int lane) {
;     const int nblk = N / 32, kb = item / nblk, nb = item % nblk, k0 = 64 * kb, n0 = 32 * nb;
; #pragma unroll 8
;     for (int i = 0; i < 32; ++i) { const int kk = 2 * i + (lane >> 5); scr[kk * 33 + (lane & 31)] = W[(size_t)(k0 + kk) * N + n0 + (lane & 31)]; }
.LBB0_841:
	s_lshl_b32 s10, s5, 1
	s_lshl_b32 s7, s4, 1
	v_or_b32_e32 v18, s10, v0
	v_or_b32_e32 v20, s7, v7
	v_mad_i64_i32 v[18:19], s[98:99], v18, s31, v[10:11]
	v_mad_i64_i32 v[20:21], s[98:99], v20, s31, v[10:11]
	global_load_dword v44, v[18:19], off
	global_load_dword v45, v[20:21], off
	s_add_i32 s14, s10, 4
	s_add_i32 s11, s7, 4
	v_or_b32_e32 v18, s14, v0
	v_or_b32_e32 v20, s11, v7
	v_mad_i64_i32 v[18:19], s[98:99], v18, s31, v[10:11]
	v_mad_i64_i32 v[20:21], s[98:99], v20, s31, v[10:11]
	global_load_dword v46, v[18:19], off
	global_load_dword v47, v[20:21], off
	s_add_i32 s14, s10, 8
	s_add_i32 s11, s7, 8
	v_or_b32_e32 v18, s14, v0
	v_or_b32_e32 v20, s11, v7
	v_mad_i64_i32 v[18:19], s[98:99], v18, s31, v[10:11]
	v_mad_i64_i32 v[20:21], s[98:99], v20, s31, v[10:11]
	global_load_dword v48, v[18:19], off
	global_load_dword v49, v[20:21], off
	s_add_i32 s14, s10, 12
	s_add_i32 s11, s7, 12
	v_or_b32_e32 v18, s14, v0
	v_or_b32_e32 v20, s11, v7
	v_mad_i64_i32 v[18:19], s[98:99], v18, s31, v[10:11]
	v_mad_i64_i32 v[20:21], s[98:99], v20, s31, v[10:11]
	global_load_dword v50, v[18:19], off
	global_load_dword v51, v[20:21], off
	s_add_i32 s14, s10, 16
	s_add_i32 s11, s7, 16
	v_or_b32_e32 v18, s14, v0
	v_or_b32_e32 v20, s11, v7
	v_mad_i64_i32 v[18:19], s[98:99], v18, s31, v[10:11]
	v_mad_i64_i32 v[20:21], s[98:99], v20, s31, v[10:11]
	global_load_dword v52, v[18:19], off
	global_load_dword v53, v[20:21], off
	s_add_i32 s14, s10, 20
	s_add_i32 s11, s7, 20
	v_or_b32_e32 v18, s14, v0
	v_or_b32_e32 v20, s11, v7
	v_mad_i64_i32 v[18:19], s[98:99], v18, s31, v[10:11]
	v_mad_i64_i32 v[20:21], s[98:99], v20, s31, v[10:11]
	global_load_dword v54, v[18:19], off
	global_load_dword v55, v[20:21], off
	s_add_i32 s14, s10, 24
	s_add_i32 s11, s7, 24
	v_or_b32_e32 v18, s14, v0
	v_or_b32_e32 v20, s11, v7
	v_mad_i64_i32 v[18:19], s[98:99], v18, s31, v[10:11]
	v_mad_i64_i32 v[20:21], s[98:99], v20, s31, v[10:11]
	global_load_dword v56, v[18:19], off
	global_load_dword v57, v[20:21], off
	s_add_i32 s14, s10, 28
	s_add_i32 s11, s7, 28
	v_or_b32_e32 v18, s14, v0
	v_or_b32_e32 v20, s11, v7
	v_mad_i64_i32 v[18:19], s[98:99], v18, s31, v[10:11]
	v_mad_i64_i32 v[20:21], s[98:99], v20, s31, v[10:11]
	global_load_dword v58, v[18:19], off
	global_load_dword v59, v[20:21], off
	s_add_i32 s5, s5, 16
	s_add_i32 s4, s4, 16
	s_add_i32 s6, s6, -16
	v_or_b32_e32 v22, s10, v2
	v_or_b32_e32 v17, s7, v3
	v_mad_u64_u32 v[18:19], s[98:99], v22, s83, v[6:7]
	v_mad_u64_u32 v[20:21], s[98:99], v17, s83, v[6:7]
	s_waitcnt vmcnt(15)
	ds_write_b32 v18, v44
	s_waitcnt vmcnt(14)
	ds_write_b32 v20, v45
	s_add_i32 s14, s10, 4
	s_add_i32 s11, s7, 4
	v_or_b32_e32 v22, s14, v2
	v_or_b32_e32 v17, s11, v3
	v_mad_u64_u32 v[18:19], s[98:99], v22, s83, v[6:7]
	v_mad_u64_u32 v[20:21], s[98:99], v17, s83, v[6:7]
	s_waitcnt vmcnt(13)
	ds_write_b32 v18, v46
	s_waitcnt vmcnt(12)
	ds_write_b32 v20, v47
	s_add_i32 s14, s10, 8
	s_add_i32 s11, s7, 8
	v_or_b32_e32 v22, s14, v2
	v_or_b32_e32 v17, s11, v3
	v_mad_u64_u32 v[18:19], s[98:99], v22, s83, v[6:7]
	v_mad_u64_u32 v[20:21], s[98:99], v17, s83, v[6:7]
	s_waitcnt vmcnt(11)
	ds_write_b32 v18, v48
	s_waitcnt vmcnt(10)
	ds_write_b32 v20, v49
	s_add_i32 s14, s10, 12
	s_add_i32 s11, s7, 12
	v_or_b32_e32 v22, s14, v2
	v_or_b32_e32 v17, s11, v3
	v_mad_u64_u32 v[18:19], s[98:99], v22, s83, v[6:7]
	v_mad_u64_u32 v[20:21], s[98:99], v17, s83, v[6:7]
	s_waitcnt vmcnt(9)
	ds_write_b32 v18, v50
	s_waitcnt vmcnt(8)
	ds_write_b32 v20, v51
	s_add_i32 s14, s10, 16
	s_add_i32 s11, s7, 16
	v_or_b32_e32 v22, s14, v2
	v_or_b32_e32 v17, s11, v3
	v_mad_u64_u32 v[18:19], s[98:99], v22, s83, v[6:7]
	v_mad_u64_u32 v[20:21], s[98:99], v17, s83, v[6:7]
	s_waitcnt vmcnt(7)
	ds_write_b32 v18, v52
	s_waitcnt vmcnt(6)
	ds_write_b32 v20, v53
	s_add_i32 s14, s10, 20
	s_add_i32 s11, s7, 20
	v_or_b32_e32 v22, s14, v2
	v_or_b32_e32 v17, s11, v3
	v_mad_u64_u32 v[18:19], s[98:99], v22, s83, v[6:7]
	v_mad_u64_u32 v[20:21], s[98:99], v17, s83, v[6:7]
	s_waitcnt vmcnt(5)
	ds_write_b32 v18, v54
	s_waitcnt vmcnt(4)
	ds_write_b32 v20, v55
	s_add_i32 s14, s10, 24
	s_add_i32 s11, s7, 24
	v_or_b32_e32 v22, s14, v2
	v_or_b32_e32 v17, s11, v3
	v_mad_u64_u32 v[18:19], s[98:99], v22, s83, v[6:7]
	v_mad_u64_u32 v[20:21], s[98:99], v17, s83, v[6:7]
	s_waitcnt vmcnt(3)
	ds_write_b32 v18, v56
	s_waitcnt vmcnt(2)
	ds_write_b32 v20, v57
	s_add_i32 s14, s10, 28
	s_add_i32 s11, s7, 28
	v_or_b32_e32 v22, s14, v2
	v_or_b32_e32 v17, s11, v3
	v_mad_u64_u32 v[18:19], s[98:99], v22, s83, v[6:7]
	v_mad_u64_u32 v[20:21], s[98:99], v17, s83, v[6:7]
	s_waitcnt vmcnt(1)
	ds_write_b32 v18, v58
	s_waitcnt vmcnt(0)
	ds_write_b32 v20, v59
	s_cmp_lg_u32 s6, 0
	s_cbranch_scc1 .LBB0_841
; #define LAS __attribute__((address_space(3)))
; __device__ __forceinline__ unsigned pkbf(float lo, float hi) { f32x2 v = {lo, hi}; bf16x2v b = __builtin_convertvector(v, bf16x2v); return __builtin_bit_cast(unsigned, b); }
; template <int MODE> __device__ __forceinline__ void transpose_item(const float* W, int K, int N, bf16_t* WT, LAS float* scr, int item, int lane) {
;     ...
;     asm volatile("s_waitcnt lgkmcnt(0)" ::: "memory");
;     const int c = lane & 7;
; #pragma unroll
;     for (int j = 0; j < 4; ++j) {
;         const int n = (lane >> 3) + 8 * j, gn = n0 + n; const LAS float* s = scr + (8 * c) * 33 + n;
;         const int drow = MODE == 0 ? gn : (MODE == 1 ? (gn >= 8608 ? gn + 96 : gn) : (gn < DFF ? 2 * gn : 2 * (gn - DFF) + 1));
;         u32x4 o; o.x = pkbf(s[0 * 33], s[1 * 33]); o.y = pkbf(s[2 * 33], s[3 * 33]); o.z = pkbf(s[4 * 33], s[5 * 33]); o.w = pkbf(s[6 * 33], s[7 * 33]);
;         *(u32x4*)(WT + (size_t)drow * K + k0 + 8 * c) = o;
;     }
;     asm volatile("s_waitcnt lgkmcnt(0)" ::: "memory");
; __device__ __forceinline__ void ph_wconv(CArgs& a, int l, unsigned char* ldsg, int gw, int ngw, int lane, int wv, int mask) {
;     ...
;     if (mask & 8) for (int it = gw; it < I_WI; it += ngw) transpose_item<2>(a.in[31] + (size_t)l * 1024 * 5632, 1024, 5632, (bf16_t*)(ws + WS_WI), scr, it, lane);
	s_waitcnt lgkmcnt(0)
	v_or_b32_e32 v0, s40, v12
	v_cmp_gt_i32_e32 vcc, s30, v0
	v_lshlrev_b32_e32 v0, 1, v0
	ds_read2_b32 v[24:25], v13 offset0:33 offset1:41
	ds_read2_b32 v[26:27], v13 offset1:8
	ds_read2_b32 v[28:29], v13 offset0:66 offset1:74
	ds_read2_b32 v[30:31], v13 offset0:99 offset1:107
	ds_read2_b32 v[32:33], v13 offset0:132 offset1:140
	ds_read2_b32 v[34:35], v13 offset0:165 offset1:173
	ds_read2_b32 v[36:37], v13 offset0:198 offset1:206
	ds_read2_b32 v[38:39], v13 offset0:231 offset1:239
	v_add_u32_e32 v7, 0xffffea01, v0
	v_cndmask_b32_e32 v22, v7, v0, vcc
	s_ashr_i32 s43, s42, 31
	v_ashrrev_i32_e32 v23, 31, v22
	v_or_b32_e32 v0, s40, v14
	v_lshl_add_u64 v[10:11], s[42:43], 1, v[8:9]
	v_lshlrev_b64 v[22:23], 11, v[22:23]
	v_cmp_gt_i32_e32 vcc, s30, v0
	v_lshlrev_b32_e32 v0, 1, v0
	s_waitcnt lgkmcnt(6)
	v_cvt_pk_bf16_f32 v18, v26, v24
	s_waitcnt lgkmcnt(4)
	v_cvt_pk_bf16_f32 v19, v28, v30
	s_waitcnt lgkmcnt(2)
	v_cvt_pk_bf16_f32 v20, v32, v34
	s_waitcnt lgkmcnt(0)
	v_cvt_pk_bf16_f32 v21, v36, v38
	v_lshl_add_u64 v[22:23], v[10:11], 0, v[22:23]
	v_add_u32_e32 v7, 0xffffea01, v0
	global_store_dwordx4 v[22:23], v[18:21], off
	v_cndmask_b32_e32 v22, v7, v0, vcc
	v_ashrrev_i32_e32 v23, 31, v22
	v_lshlrev_b64 v[22:23], 11, v[22:23]
	v_cvt_pk_bf16_f32 v18, v27, v25
	v_cvt_pk_bf16_f32 v19, v29, v31
	v_cvt_pk_bf16_f32 v20, v33, v35
	v_cvt_pk_bf16_f32 v21, v37, v39
	v_lshl_add_u64 v[22:23], v[10:11], 0, v[22:23]
	global_store_dwordx4 v[22:23], v[18:21], off
	v_or_b32_e32 v0, s40, v15
	v_cmp_gt_i32_e32 vcc, s30, v0
	v_lshlrev_b32_e32 v0, 1, v0
	ds_read2_b32 v[24:25], v13 offset0:49 offset1:57
	ds_read2_b32 v[26:27], v13 offset0:16 offset1:24
	ds_read2_b32 v[28:29], v13 offset0:82 offset1:90
	ds_read2_b32 v[30:31], v13 offset0:115 offset1:123
	ds_read2_b32 v[32:33], v13 offset0:148 offset1:156
	ds_read2_b32 v[34:35], v13 offset0:181 offset1:189
	ds_read2_b32 v[36:37], v13 offset0:214 offset1:222
	ds_read2_b32 v[38:39], v13 offset0:247 offset1:255
	v_add_u32_e32 v7, 0xffffea01, v0
	v_cndmask_b32_e32 v22, v7, v0, vcc
	v_ashrrev_i32_e32 v23, 31, v22
	v_or_b32_e32 v0, s40, v16
	v_lshlrev_b64 v[22:23], 11, v[22:23]
	v_cmp_gt_i32_e32 vcc, s30, v0
	v_lshlrev_b32_e32 v0, 1, v0
	s_waitcnt lgkmcnt(6)
	v_cvt_pk_bf16_f32 v18, v26, v24
	s_waitcnt lgkmcnt(4)
	v_cvt_pk_bf16_f32 v19, v28, v30
	s_waitcnt lgkmcnt(2)
	v_cvt_pk_bf16_f32 v20, v32, v34
	s_waitcnt lgkmcnt(0)
	v_cvt_pk_bf16_f32 v21, v36, v38
	v_lshl_add_u64 v[22:23], v[10:11], 0, v[22:23]
	v_add_u32_e32 v7, 0xffffea01, v0
	global_store_dwordx4 v[22:23], v[18:21], off
	v_cndmask_b32_e32 v22, v7, v0, vcc
	v_ashrrev_i32_e32 v23, 31, v22
	v_lshlrev_b64 v[22:23], 11, v[22:23]
	v_cvt_pk_bf16_f32 v18, v27, v25
	v_cvt_pk_bf16_f32 v19, v29, v31
	v_cvt_pk_bf16_f32 v20, v33, v35
	v_cvt_pk_bf16_f32 v21, v37, v39
	v_lshl_add_u64 v[10:11], v[10:11], 0, v[22:23]
	global_store_dwordx4 v[10:11], v[18:21], off
	s_waitcnt lgkmcnt(0)
	s_add_i32 s1, s1, s3
	s_cmpk_gt_i32 s1, 0xaff
	s_cbranch_scc0 .LBB0_840
